# all six large bf16 GEMM tile loops hand-written (2-deep global prefetch, fragment prefetch, locality-aware tile order); precision unchanged
# speedup vs baseline: 1.0933x; 1.0132x over previous
.LBB0_193:
.Lgin0_tile:
	s_bfe_u32 s100, s36, 0x30005
	s_and_b32 s101, s36, 31
	s_lshr_b32 s82, s36, 8
	s_lshl_b32 s64, s100, 3
	s_lshr_b32 s100, s101, 2
	s_add_u32 s64, s64, s100
	s_lshl_b32 s82, s82, 2
	s_and_b32 s101, s101, 3
	s_add_u32 s82, s82, s101
	s_lshl_b32 s64, s64, 8
	s_lshl_b32 s82, s82, 8
	s_lshl_b32 s100, s64, 12
	s_add_u32 s100, s100, 0x6224000
	s_add_u32 s48, s92, s100
	s_addc_u32 s49, s93, 0
	s_and_b32 s49, s49, 0xffff
	s_mov_b32 s50, 0x100000
	s_mov_b32 s51, 0x20000
	s_lshl_b32 s100, s82, 12
	s_add_u32 s100, s100, 0x0
	s_add_u32 s52, s92, s100
	s_addc_u32 s53, s93, 0
	s_and_b32 s53, s53, 0xffff
	s_sub_u32 s100, 0x1380, s82
	s_min_u32 s100, s100, 0x100
	s_lshl_b32 s54, s100, 12
	s_mov_b32 s55, 0x20000
	s_mov_b32 s46, 0x40000
	s_mov_b32 s47, 0x80000
	s_mov_b32 s58, 0xc0000
	v_lshrrev_b32_e32 v128, 3, v190
	v_and_b32_e32 v129, 7, v190
	v_lshlrev_b32_e32 v129, 4, v129
	v_lshl_add_u32 v160, v128, 12, v129
	v_mul_u32_u24_e32 v130, 0x90, v128
	v_add_u32_e32 v170, v130, v129
	v_add_u32_e32 v171, 0x12000, v170
	v_and_b32_e32 v131, 31, v190
	v_bfe_u32 v132, v190, 5, 1
	v_bfe_u32 v133, v190, 6, 2
	v_bfe_u32 v134, v190, 8, 1
	v_lshl_add_u32 v135, v134, 7, v131
	v_mul_u32_u24_e32 v135, 0x90, v135
	v_lshl_add_u32 v175, v132, 4, v135
	v_lshl_add_u32 v136, v133, 6, v131
	v_mul_u32_u24_e32 v136, 0x90, v136
	v_lshl_add_u32 v136, v132, 4, v136
	v_add_u32_e32 v254, 0x12000, v136
	v_mov_b32_e32 v0, 0
	v_mov_b32_e32 v1, 0
	v_mov_b32_e32 v2, 0
	v_mov_b32_e32 v3, 0
	v_mov_b32_e32 v4, 0
	v_mov_b32_e32 v5, 0
	v_mov_b32_e32 v6, 0
	v_mov_b32_e32 v7, 0
	v_mov_b32_e32 v8, 0
	v_mov_b32_e32 v9, 0
	v_mov_b32_e32 v10, 0
	v_mov_b32_e32 v11, 0
	v_mov_b32_e32 v12, 0
	v_mov_b32_e32 v13, 0
	v_mov_b32_e32 v14, 0
	v_mov_b32_e32 v15, 0
	v_mov_b32_e32 v16, 0
	v_mov_b32_e32 v17, 0
	v_mov_b32_e32 v18, 0
	v_mov_b32_e32 v19, 0
	v_mov_b32_e32 v20, 0
	v_mov_b32_e32 v21, 0
	v_mov_b32_e32 v22, 0
	v_mov_b32_e32 v23, 0
	v_mov_b32_e32 v24, 0
	v_mov_b32_e32 v25, 0
	v_mov_b32_e32 v26, 0
	v_mov_b32_e32 v27, 0
	v_mov_b32_e32 v28, 0
	v_mov_b32_e32 v29, 0
	v_mov_b32_e32 v30, 0
	v_mov_b32_e32 v31, 0
	v_mov_b32_e32 v32, 0
	v_mov_b32_e32 v33, 0
	v_mov_b32_e32 v34, 0
	v_mov_b32_e32 v35, 0
	v_mov_b32_e32 v36, 0
	v_mov_b32_e32 v37, 0
	v_mov_b32_e32 v38, 0
	v_mov_b32_e32 v39, 0
	v_mov_b32_e32 v40, 0
	v_mov_b32_e32 v41, 0
	v_mov_b32_e32 v42, 0
	v_mov_b32_e32 v43, 0
	v_mov_b32_e32 v44, 0
	v_mov_b32_e32 v45, 0
	v_mov_b32_e32 v46, 0
	v_mov_b32_e32 v47, 0
	v_mov_b32_e32 v48, 0
	v_mov_b32_e32 v49, 0
	v_mov_b32_e32 v50, 0
	v_mov_b32_e32 v51, 0
	v_mov_b32_e32 v52, 0
	v_mov_b32_e32 v53, 0
	v_mov_b32_e32 v54, 0
	v_mov_b32_e32 v55, 0
	v_mov_b32_e32 v56, 0
	v_mov_b32_e32 v57, 0
	v_mov_b32_e32 v58, 0
	v_mov_b32_e32 v59, 0
	v_mov_b32_e32 v60, 0
	v_mov_b32_e32 v61, 0
	v_mov_b32_e32 v62, 0
	v_mov_b32_e32 v63, 0
	v_mov_b32_e32 v64, 0
	v_mov_b32_e32 v65, 0
	v_mov_b32_e32 v66, 0
	v_mov_b32_e32 v67, 0
	v_mov_b32_e32 v68, 0
	v_mov_b32_e32 v69, 0
	v_mov_b32_e32 v70, 0
	v_mov_b32_e32 v71, 0
	v_mov_b32_e32 v72, 0
	v_mov_b32_e32 v73, 0
	v_mov_b32_e32 v74, 0
	v_mov_b32_e32 v75, 0
	v_mov_b32_e32 v76, 0
	v_mov_b32_e32 v77, 0
	v_mov_b32_e32 v78, 0
	v_mov_b32_e32 v79, 0
	v_mov_b32_e32 v80, 0
	v_mov_b32_e32 v81, 0
	v_mov_b32_e32 v82, 0
	v_mov_b32_e32 v83, 0
	v_mov_b32_e32 v84, 0
	v_mov_b32_e32 v85, 0
	v_mov_b32_e32 v86, 0
	v_mov_b32_e32 v87, 0
	v_mov_b32_e32 v88, 0
	v_mov_b32_e32 v89, 0
	v_mov_b32_e32 v90, 0
	v_mov_b32_e32 v91, 0
	v_mov_b32_e32 v92, 0
	v_mov_b32_e32 v93, 0
	v_mov_b32_e32 v94, 0
	v_mov_b32_e32 v95, 0
	v_mov_b32_e32 v96, 0
	v_mov_b32_e32 v97, 0
	v_mov_b32_e32 v98, 0
	v_mov_b32_e32 v99, 0
	v_mov_b32_e32 v100, 0
	v_mov_b32_e32 v101, 0
	v_mov_b32_e32 v102, 0
	v_mov_b32_e32 v103, 0
	v_mov_b32_e32 v104, 0
	v_mov_b32_e32 v105, 0
	v_mov_b32_e32 v106, 0
	v_mov_b32_e32 v107, 0
	v_mov_b32_e32 v108, 0
	v_mov_b32_e32 v109, 0
	v_mov_b32_e32 v110, 0
	v_mov_b32_e32 v111, 0
	v_mov_b32_e32 v112, 0
	v_mov_b32_e32 v113, 0
	v_mov_b32_e32 v114, 0
	v_mov_b32_e32 v115, 0
	v_mov_b32_e32 v116, 0
	v_mov_b32_e32 v117, 0
	v_mov_b32_e32 v118, 0
	v_mov_b32_e32 v119, 0
	v_mov_b32_e32 v120, 0
	v_mov_b32_e32 v121, 0
	v_mov_b32_e32 v122, 0
	v_mov_b32_e32 v123, 0
	v_mov_b32_e32 v124, 0
	v_mov_b32_e32 v125, 0
	v_mov_b32_e32 v126, 0
	v_mov_b32_e32 v127, 0
	v_mov_b32_e32 v192, 0
	v_mov_b32_e32 v193, 0
	v_mov_b32_e32 v194, 0
	v_mov_b32_e32 v195, 0
	v_mov_b32_e32 v196, 0
	v_mov_b32_e32 v197, 0
	v_mov_b32_e32 v198, 0
	v_mov_b32_e32 v199, 0
	v_mov_b32_e32 v200, 0
	v_mov_b32_e32 v201, 0
	v_mov_b32_e32 v202, 0
	v_mov_b32_e32 v203, 0
	v_mov_b32_e32 v204, 0
	v_mov_b32_e32 v205, 0
	v_mov_b32_e32 v206, 0
	v_mov_b32_e32 v207, 0
	v_mov_b32_e32 v208, 0
	v_mov_b32_e32 v209, 0
	v_mov_b32_e32 v210, 0
	v_mov_b32_e32 v211, 0
	v_mov_b32_e32 v212, 0
	v_mov_b32_e32 v213, 0
	v_mov_b32_e32 v214, 0
	v_mov_b32_e32 v215, 0
	v_mov_b32_e32 v188, 0
	v_mov_b32_e32 v189, 0
	buffer_load_dwordx4 v[216:219], v160, s[48:51], 0 offen
	buffer_load_dwordx4 v[220:223], v160, s[48:51], s46 offen
	buffer_load_dwordx4 v[224:227], v160, s[48:51], s47 offen
	buffer_load_dwordx4 v[228:231], v160, s[48:51], s58 offen
	buffer_load_dwordx4 v[232:235], v160, s[52:55], 0 offen
	buffer_load_dwordx4 v[236:239], v160, s[52:55], s46 offen
	buffer_load_dwordx4 v[152:155], v160, s[52:55], s47 offen
	buffer_load_dwordx4 v[156:159], v160, s[52:55], s58 offen
	v_add_u32_e32 v160, 0x80, v160
	buffer_load_dwordx4 v[162:165], v160, s[48:51], 0 offen
	buffer_load_dwordx4 v[166:169], v160, s[48:51], s46 offen
	buffer_load_dwordx4 v[176:179], v160, s[48:51], s47 offen
	buffer_load_dwordx4 v[180:183], v160, s[48:51], s58 offen
	buffer_load_dwordx4 v[184:187], v160, s[52:55], 0 offen
	buffer_load_dwordx4 v[242:245], v160, s[52:55], s46 offen
	buffer_load_dwordx4 v[246:249], v160, s[52:55], s47 offen
	buffer_load_dwordx4 v[250:253], v160, s[52:55], s58 offen
	v_add_u32_e32 v160, 0x80, v160
	s_waitcnt vmcnt(8)
	ds_write_b128 v170, v[216:219] offset:0
	ds_write_b128 v170, v[220:223] offset:9216
	ds_write_b128 v170, v[224:227] offset:18432
	ds_write_b128 v170, v[228:231] offset:27648
	ds_write_b128 v171, v[232:235] offset:0
	ds_write_b128 v171, v[236:239] offset:9216
	ds_write_b128 v171, v[152:155] offset:18432
	ds_write_b128 v171, v[156:159] offset:27648
	buffer_load_dwordx4 v[216:219], v160, s[48:51], 0 offen
	buffer_load_dwordx4 v[220:223], v160, s[48:51], s46 offen
	buffer_load_dwordx4 v[224:227], v160, s[48:51], s47 offen
	buffer_load_dwordx4 v[228:231], v160, s[48:51], s58 offen
	buffer_load_dwordx4 v[232:235], v160, s[52:55], 0 offen
	buffer_load_dwordx4 v[236:239], v160, s[52:55], s46 offen
	buffer_load_dwordx4 v[152:155], v160, s[52:55], s47 offen
	buffer_load_dwordx4 v[156:159], v160, s[52:55], s58 offen
	v_add_u32_e32 v160, 0x80, v160
	s_waitcnt lgkmcnt(0)
	s_barrier
	s_movk_i32 s59, 14
.Lgin0_loop:
	ds_read_b128 v[144:147], v254 offset:0
	ds_read_b128 v[148:151], v254 offset:4608
	ds_read_b128 v[128:131], v175 offset:0
	ds_read_b128 v[132:135], v175 offset:4608
	ds_read_b128 v[136:139], v175 offset:9216
	ds_read_b128 v[140:143], v175 offset:13824
	v_mfma_f32_32x32x16_bf16 v[112:127], v[192:195], v[208:211], v[112:127]
	s_waitcnt vmcnt(8)
	v_mfma_f32_32x32x16_bf16 v[96:111], v[192:195], v[212:215], v[96:111]
	ds_write_b128 v170, v[162:165] offset:36864
	v_mfma_f32_32x32x16_bf16 v[80:95], v[196:199], v[208:211], v[80:95]
	ds_write_b128 v170, v[166:169] offset:46080
	v_mfma_f32_32x32x16_bf16 v[64:79], v[196:199], v[212:215], v[64:79]
	ds_write_b128 v170, v[176:179] offset:55296
	v_mfma_f32_32x32x16_bf16 v[48:63], v[200:203], v[208:211], v[48:63]
	ds_write_b128 v170, v[180:183] offset:64512
	v_mfma_f32_32x32x16_bf16 v[32:47], v[200:203], v[212:215], v[32:47]
	ds_write_b128 v171, v[184:187] offset:36864
	v_mfma_f32_32x32x16_bf16 v[16:31], v[204:207], v[208:211], v[16:31]
	ds_write_b128 v171, v[242:245] offset:46080
	v_mfma_f32_32x32x16_bf16 v[0:15], v[204:207], v[212:215], v[0:15]
	ds_write_b128 v171, v[246:249] offset:55296
	ds_write_b128 v171, v[250:253] offset:64512
	s_waitcnt lgkmcnt(8)
	v_mfma_f32_32x32x16_bf16 v[112:127], v[128:131], v[144:147], v[112:127]
	ds_read_b128 v[208:211], v254 offset:32
	v_mfma_f32_32x32x16_bf16 v[96:111], v[128:131], v[148:151], v[96:111]
	ds_read_b128 v[212:215], v254 offset:4640
	ds_read_b128 v[192:195], v175 offset:32
	v_mfma_f32_32x32x16_bf16 v[80:95], v[132:135], v[144:147], v[80:95]
	ds_read_b128 v[196:199], v175 offset:4640
	ds_read_b128 v[200:203], v175 offset:9248
	v_mfma_f32_32x32x16_bf16 v[64:79], v[132:135], v[148:151], v[64:79]
	ds_read_b128 v[204:207], v175 offset:13856
	buffer_load_dwordx4 v[162:165], v160, s[48:51], 0 offen
	v_mfma_f32_32x32x16_bf16 v[48:63], v[136:139], v[144:147], v[48:63]
	buffer_load_dwordx4 v[166:169], v160, s[48:51], s46 offen
	buffer_load_dwordx4 v[176:179], v160, s[48:51], s47 offen
	v_mfma_f32_32x32x16_bf16 v[32:47], v[136:139], v[148:151], v[32:47]
	buffer_load_dwordx4 v[180:183], v160, s[48:51], s58 offen
	buffer_load_dwordx4 v[184:187], v160, s[52:55], 0 offen
	v_mfma_f32_32x32x16_bf16 v[16:31], v[140:143], v[144:147], v[16:31]
	buffer_load_dwordx4 v[242:245], v160, s[52:55], s46 offen
	buffer_load_dwordx4 v[246:249], v160, s[52:55], s47 offen
	v_mfma_f32_32x32x16_bf16 v[0:15], v[140:143], v[148:151], v[0:15]
	buffer_load_dwordx4 v[250:253], v160, s[52:55], s58 offen
	v_add_u32_e32 v160, 0x80, v160
	s_waitcnt lgkmcnt(0)
	v_mfma_f32_32x32x16_bf16 v[112:127], v[192:195], v[208:211], v[112:127]
	v_mfma_f32_32x32x16_bf16 v[96:111], v[192:195], v[212:215], v[96:111]
	ds_read_b128 v[144:147], v254 offset:64
	v_mfma_f32_32x32x16_bf16 v[80:95], v[196:199], v[208:211], v[80:95]
	ds_read_b128 v[148:151], v254 offset:4672
	v_mfma_f32_32x32x16_bf16 v[64:79], v[196:199], v[212:215], v[64:79]
	ds_read_b128 v[128:131], v175 offset:64
	v_mfma_f32_32x32x16_bf16 v[48:63], v[200:203], v[208:211], v[48:63]
	v_mfma_f32_32x32x16_bf16 v[32:47], v[200:203], v[212:215], v[32:47]
	ds_read_b128 v[132:135], v175 offset:4672
	v_mfma_f32_32x32x16_bf16 v[16:31], v[204:207], v[208:211], v[16:31]
	ds_read_b128 v[136:139], v175 offset:9280
	v_mfma_f32_32x32x16_bf16 v[0:15], v[204:207], v[212:215], v[0:15]
	ds_read_b128 v[140:143], v175 offset:13888
	s_waitcnt lgkmcnt(0)
	v_mfma_f32_32x32x16_bf16 v[112:127], v[128:131], v[144:147], v[112:127]
	v_mfma_f32_32x32x16_bf16 v[96:111], v[128:131], v[148:151], v[96:111]
	ds_read_b128 v[208:211], v254 offset:96
	v_mfma_f32_32x32x16_bf16 v[80:95], v[132:135], v[144:147], v[80:95]
	ds_read_b128 v[212:215], v254 offset:4704
	v_mfma_f32_32x32x16_bf16 v[64:79], v[132:135], v[148:151], v[64:79]
	ds_read_b128 v[192:195], v175 offset:96
	v_mfma_f32_32x32x16_bf16 v[48:63], v[136:139], v[144:147], v[48:63]
	v_mfma_f32_32x32x16_bf16 v[32:47], v[136:139], v[148:151], v[32:47]
	ds_read_b128 v[196:199], v175 offset:4704
	v_mfma_f32_32x32x16_bf16 v[16:31], v[140:143], v[144:147], v[16:31]
	ds_read_b128 v[200:203], v175 offset:9312
	v_mfma_f32_32x32x16_bf16 v[0:15], v[140:143], v[148:151], v[0:15]
	ds_read_b128 v[204:207], v175 offset:13920
	s_waitcnt lgkmcnt(0)
	s_barrier
	ds_read_b128 v[144:147], v254 offset:36864
	ds_read_b128 v[148:151], v254 offset:41472
	ds_read_b128 v[128:131], v175 offset:36864
	ds_read_b128 v[132:135], v175 offset:41472
	ds_read_b128 v[136:139], v175 offset:46080
	ds_read_b128 v[140:143], v175 offset:50688
	v_mfma_f32_32x32x16_bf16 v[112:127], v[192:195], v[208:211], v[112:127]
	s_waitcnt vmcnt(8)
	v_mfma_f32_32x32x16_bf16 v[96:111], v[192:195], v[212:215], v[96:111]
	ds_write_b128 v170, v[216:219] offset:0
	v_mfma_f32_32x32x16_bf16 v[80:95], v[196:199], v[208:211], v[80:95]
	ds_write_b128 v170, v[220:223] offset:9216
	v_mfma_f32_32x32x16_bf16 v[64:79], v[196:199], v[212:215], v[64:79]
	ds_write_b128 v170, v[224:227] offset:18432
	v_mfma_f32_32x32x16_bf16 v[48:63], v[200:203], v[208:211], v[48:63]
	ds_write_b128 v170, v[228:231] offset:27648
	v_mfma_f32_32x32x16_bf16 v[32:47], v[200:203], v[212:215], v[32:47]
	ds_write_b128 v171, v[232:235] offset:0
	v_mfma_f32_32x32x16_bf16 v[16:31], v[204:207], v[208:211], v[16:31]
	ds_write_b128 v171, v[236:239] offset:9216
	v_mfma_f32_32x32x16_bf16 v[0:15], v[204:207], v[212:215], v[0:15]
	ds_write_b128 v171, v[152:155] offset:18432
	ds_write_b128 v171, v[156:159] offset:27648
	s_waitcnt lgkmcnt(8)
	v_mfma_f32_32x32x16_bf16 v[112:127], v[128:131], v[144:147], v[112:127]
	ds_read_b128 v[208:211], v254 offset:36896
	v_mfma_f32_32x32x16_bf16 v[96:111], v[128:131], v[148:151], v[96:111]
	ds_read_b128 v[212:215], v254 offset:41504
	ds_read_b128 v[192:195], v175 offset:36896
	v_mfma_f32_32x32x16_bf16 v[80:95], v[132:135], v[144:147], v[80:95]
	ds_read_b128 v[196:199], v175 offset:41504
	ds_read_b128 v[200:203], v175 offset:46112
	v_mfma_f32_32x32x16_bf16 v[64:79], v[132:135], v[148:151], v[64:79]
	ds_read_b128 v[204:207], v175 offset:50720
	buffer_load_dwordx4 v[216:219], v160, s[48:51], 0 offen
	v_mfma_f32_32x32x16_bf16 v[48:63], v[136:139], v[144:147], v[48:63]
	buffer_load_dwordx4 v[220:223], v160, s[48:51], s46 offen
	buffer_load_dwordx4 v[224:227], v160, s[48:51], s47 offen
	v_mfma_f32_32x32x16_bf16 v[32:47], v[136:139], v[148:151], v[32:47]
	buffer_load_dwordx4 v[228:231], v160, s[48:51], s58 offen
	buffer_load_dwordx4 v[232:235], v160, s[52:55], 0 offen
	v_mfma_f32_32x32x16_bf16 v[16:31], v[140:143], v[144:147], v[16:31]
	buffer_load_dwordx4 v[236:239], v160, s[52:55], s46 offen
	buffer_load_dwordx4 v[152:155], v160, s[52:55], s47 offen
	v_mfma_f32_32x32x16_bf16 v[0:15], v[140:143], v[148:151], v[0:15]
	buffer_load_dwordx4 v[156:159], v160, s[52:55], s58 offen
	v_add_u32_e32 v160, 0x80, v160
	s_waitcnt lgkmcnt(0)
	v_mfma_f32_32x32x16_bf16 v[112:127], v[192:195], v[208:211], v[112:127]
	v_mfma_f32_32x32x16_bf16 v[96:111], v[192:195], v[212:215], v[96:111]
	ds_read_b128 v[144:147], v254 offset:36928
	v_mfma_f32_32x32x16_bf16 v[80:95], v[196:199], v[208:211], v[80:95]
	ds_read_b128 v[148:151], v254 offset:41536
	v_mfma_f32_32x32x16_bf16 v[64:79], v[196:199], v[212:215], v[64:79]
	ds_read_b128 v[128:131], v175 offset:36928
	v_mfma_f32_32x32x16_bf16 v[48:63], v[200:203], v[208:211], v[48:63]
	v_mfma_f32_32x32x16_bf16 v[32:47], v[200:203], v[212:215], v[32:47]
	ds_read_b128 v[132:135], v175 offset:41536
	v_mfma_f32_32x32x16_bf16 v[16:31], v[204:207], v[208:211], v[16:31]
	ds_read_b128 v[136:139], v175 offset:46144
	v_mfma_f32_32x32x16_bf16 v[0:15], v[204:207], v[212:215], v[0:15]
	ds_read_b128 v[140:143], v175 offset:50752
	s_waitcnt lgkmcnt(0)
	v_mfma_f32_32x32x16_bf16 v[112:127], v[128:131], v[144:147], v[112:127]
	v_mfma_f32_32x32x16_bf16 v[96:111], v[128:131], v[148:151], v[96:111]
	ds_read_b128 v[208:211], v254 offset:36960
	v_mfma_f32_32x32x16_bf16 v[80:95], v[132:135], v[144:147], v[80:95]
	ds_read_b128 v[212:215], v254 offset:41568
	v_mfma_f32_32x32x16_bf16 v[64:79], v[132:135], v[148:151], v[64:79]
	ds_read_b128 v[192:195], v175 offset:36960
	v_mfma_f32_32x32x16_bf16 v[48:63], v[136:139], v[144:147], v[48:63]
	v_mfma_f32_32x32x16_bf16 v[32:47], v[136:139], v[148:151], v[32:47]
	ds_read_b128 v[196:199], v175 offset:41568
	v_mfma_f32_32x32x16_bf16 v[16:31], v[140:143], v[144:147], v[16:31]
	ds_read_b128 v[200:203], v175 offset:46176
	v_mfma_f32_32x32x16_bf16 v[0:15], v[140:143], v[148:151], v[0:15]
	ds_read_b128 v[204:207], v175 offset:50784
	s_waitcnt lgkmcnt(0)
	s_barrier
	s_add_i32 s59, s59, -1
	s_cmp_lg_u32 s59, 0
	s_cbranch_scc1 .Lgin0_loop
	ds_read_b128 v[144:147], v254 offset:0
	ds_read_b128 v[148:151], v254 offset:4608
	ds_read_b128 v[128:131], v175 offset:0
	ds_read_b128 v[132:135], v175 offset:4608
	ds_read_b128 v[136:139], v175 offset:9216
	ds_read_b128 v[140:143], v175 offset:13824
	v_mfma_f32_32x32x16_bf16 v[112:127], v[192:195], v[208:211], v[112:127]
	s_waitcnt vmcnt(8)
	v_mfma_f32_32x32x16_bf16 v[96:111], v[192:195], v[212:215], v[96:111]
	ds_write_b128 v170, v[162:165] offset:36864
	v_mfma_f32_32x32x16_bf16 v[80:95], v[196:199], v[208:211], v[80:95]
	ds_write_b128 v170, v[166:169] offset:46080
	v_mfma_f32_32x32x16_bf16 v[64:79], v[196:199], v[212:215], v[64:79]
	ds_write_b128 v170, v[176:179] offset:55296
	v_mfma_f32_32x32x16_bf16 v[48:63], v[200:203], v[208:211], v[48:63]
	ds_write_b128 v170, v[180:183] offset:64512
	v_mfma_f32_32x32x16_bf16 v[32:47], v[200:203], v[212:215], v[32:47]
	ds_write_b128 v171, v[184:187] offset:36864
	v_mfma_f32_32x32x16_bf16 v[16:31], v[204:207], v[208:211], v[16:31]
	ds_write_b128 v171, v[242:245] offset:46080
	v_mfma_f32_32x32x16_bf16 v[0:15], v[204:207], v[212:215], v[0:15]
	ds_write_b128 v171, v[246:249] offset:55296
	ds_write_b128 v171, v[250:253] offset:64512
	s_waitcnt lgkmcnt(8)
	v_mfma_f32_32x32x16_bf16 v[112:127], v[128:131], v[144:147], v[112:127]
	ds_read_b128 v[208:211], v254 offset:32
	v_mfma_f32_32x32x16_bf16 v[96:111], v[128:131], v[148:151], v[96:111]
	ds_read_b128 v[212:215], v254 offset:4640
	ds_read_b128 v[192:195], v175 offset:32
	v_mfma_f32_32x32x16_bf16 v[80:95], v[132:135], v[144:147], v[80:95]
	ds_read_b128 v[196:199], v175 offset:4640
	ds_read_b128 v[200:203], v175 offset:9248
	v_mfma_f32_32x32x16_bf16 v[64:79], v[132:135], v[148:151], v[64:79]
	ds_read_b128 v[204:207], v175 offset:13856
	buffer_load_dwordx4 v[162:165], v160, s[48:51], 0 offen
	v_mfma_f32_32x32x16_bf16 v[48:63], v[136:139], v[144:147], v[48:63]
	buffer_load_dwordx4 v[166:169], v160, s[48:51], s46 offen
	buffer_load_dwordx4 v[176:179], v160, s[48:51], s47 offen
	v_mfma_f32_32x32x16_bf16 v[32:47], v[136:139], v[148:151], v[32:47]
	buffer_load_dwordx4 v[180:183], v160, s[48:51], s58 offen
	buffer_load_dwordx4 v[184:187], v160, s[52:55], 0 offen
	v_mfma_f32_32x32x16_bf16 v[16:31], v[140:143], v[144:147], v[16:31]
	buffer_load_dwordx4 v[242:245], v160, s[52:55], s46 offen
	buffer_load_dwordx4 v[246:249], v160, s[52:55], s47 offen
	v_mfma_f32_32x32x16_bf16 v[0:15], v[140:143], v[148:151], v[0:15]
	buffer_load_dwordx4 v[250:253], v160, s[52:55], s58 offen
	v_add_u32_e32 v160, 0x80, v160
	s_waitcnt lgkmcnt(0)
	v_mfma_f32_32x32x16_bf16 v[112:127], v[192:195], v[208:211], v[112:127]
	v_mfma_f32_32x32x16_bf16 v[96:111], v[192:195], v[212:215], v[96:111]
	ds_read_b128 v[144:147], v254 offset:64
	v_mfma_f32_32x32x16_bf16 v[80:95], v[196:199], v[208:211], v[80:95]
	ds_read_b128 v[148:151], v254 offset:4672
	v_mfma_f32_32x32x16_bf16 v[64:79], v[196:199], v[212:215], v[64:79]
	ds_read_b128 v[128:131], v175 offset:64
	v_mfma_f32_32x32x16_bf16 v[48:63], v[200:203], v[208:211], v[48:63]
	v_mfma_f32_32x32x16_bf16 v[32:47], v[200:203], v[212:215], v[32:47]
	ds_read_b128 v[132:135], v175 offset:4672
	v_mfma_f32_32x32x16_bf16 v[16:31], v[204:207], v[208:211], v[16:31]
	ds_read_b128 v[136:139], v175 offset:9280
	v_mfma_f32_32x32x16_bf16 v[0:15], v[204:207], v[212:215], v[0:15]
	ds_read_b128 v[140:143], v175 offset:13888
	s_waitcnt lgkmcnt(0)
	v_mfma_f32_32x32x16_bf16 v[112:127], v[128:131], v[144:147], v[112:127]
	v_mfma_f32_32x32x16_bf16 v[96:111], v[128:131], v[148:151], v[96:111]
	ds_read_b128 v[208:211], v254 offset:96
	v_mfma_f32_32x32x16_bf16 v[80:95], v[132:135], v[144:147], v[80:95]
	ds_read_b128 v[212:215], v254 offset:4704
	v_mfma_f32_32x32x16_bf16 v[64:79], v[132:135], v[148:151], v[64:79]
	ds_read_b128 v[192:195], v175 offset:96
	v_mfma_f32_32x32x16_bf16 v[48:63], v[136:139], v[144:147], v[48:63]
	v_mfma_f32_32x32x16_bf16 v[32:47], v[136:139], v[148:151], v[32:47]
	ds_read_b128 v[196:199], v175 offset:4704
	v_mfma_f32_32x32x16_bf16 v[16:31], v[140:143], v[144:147], v[16:31]
	ds_read_b128 v[200:203], v175 offset:9312
	v_mfma_f32_32x32x16_bf16 v[0:15], v[140:143], v[148:151], v[0:15]
	ds_read_b128 v[204:207], v175 offset:13920
	s_waitcnt lgkmcnt(0)
	s_barrier
	ds_read_b128 v[144:147], v254 offset:36864
	ds_read_b128 v[148:151], v254 offset:41472
	ds_read_b128 v[128:131], v175 offset:36864
	ds_read_b128 v[132:135], v175 offset:41472
	ds_read_b128 v[136:139], v175 offset:46080
	ds_read_b128 v[140:143], v175 offset:50688
	v_mfma_f32_32x32x16_bf16 v[112:127], v[192:195], v[208:211], v[112:127]
	s_waitcnt vmcnt(8)
	v_mfma_f32_32x32x16_bf16 v[96:111], v[192:195], v[212:215], v[96:111]
	ds_write_b128 v170, v[216:219] offset:0
	v_mfma_f32_32x32x16_bf16 v[80:95], v[196:199], v[208:211], v[80:95]
	ds_write_b128 v170, v[220:223] offset:9216
	v_mfma_f32_32x32x16_bf16 v[64:79], v[196:199], v[212:215], v[64:79]
	ds_write_b128 v170, v[224:227] offset:18432
	v_mfma_f32_32x32x16_bf16 v[48:63], v[200:203], v[208:211], v[48:63]
	ds_write_b128 v170, v[228:231] offset:27648
	v_mfma_f32_32x32x16_bf16 v[32:47], v[200:203], v[212:215], v[32:47]
	ds_write_b128 v171, v[232:235] offset:0
	v_mfma_f32_32x32x16_bf16 v[16:31], v[204:207], v[208:211], v[16:31]
	ds_write_b128 v171, v[236:239] offset:9216
	v_mfma_f32_32x32x16_bf16 v[0:15], v[204:207], v[212:215], v[0:15]
	ds_write_b128 v171, v[152:155] offset:18432
	ds_write_b128 v171, v[156:159] offset:27648
	s_waitcnt lgkmcnt(8)
	v_mfma_f32_32x32x16_bf16 v[112:127], v[128:131], v[144:147], v[112:127]
	v_mfma_f32_32x32x16_bf16 v[96:111], v[128:131], v[148:151], v[96:111]
	ds_read_b128 v[208:211], v254 offset:36896
	v_mfma_f32_32x32x16_bf16 v[80:95], v[132:135], v[144:147], v[80:95]
	ds_read_b128 v[212:215], v254 offset:41504
	v_mfma_f32_32x32x16_bf16 v[64:79], v[132:135], v[148:151], v[64:79]
	ds_read_b128 v[192:195], v175 offset:36896
	v_mfma_f32_32x32x16_bf16 v[48:63], v[136:139], v[144:147], v[48:63]
	v_mfma_f32_32x32x16_bf16 v[32:47], v[136:139], v[148:151], v[32:47]
	ds_read_b128 v[196:199], v175 offset:41504
	v_mfma_f32_32x32x16_bf16 v[16:31], v[140:143], v[144:147], v[16:31]
	ds_read_b128 v[200:203], v175 offset:46112
	v_mfma_f32_32x32x16_bf16 v[0:15], v[140:143], v[148:151], v[0:15]
	ds_read_b128 v[204:207], v175 offset:50720
	s_waitcnt lgkmcnt(0)
	v_mfma_f32_32x32x16_bf16 v[112:127], v[192:195], v[208:211], v[112:127]
	v_mfma_f32_32x32x16_bf16 v[96:111], v[192:195], v[212:215], v[96:111]
	ds_read_b128 v[144:147], v254 offset:36928
	v_mfma_f32_32x32x16_bf16 v[80:95], v[196:199], v[208:211], v[80:95]
	ds_read_b128 v[148:151], v254 offset:41536
	v_mfma_f32_32x32x16_bf16 v[64:79], v[196:199], v[212:215], v[64:79]
	ds_read_b128 v[128:131], v175 offset:36928
	v_mfma_f32_32x32x16_bf16 v[48:63], v[200:203], v[208:211], v[48:63]
	v_mfma_f32_32x32x16_bf16 v[32:47], v[200:203], v[212:215], v[32:47]
	ds_read_b128 v[132:135], v175 offset:41536
	v_mfma_f32_32x32x16_bf16 v[16:31], v[204:207], v[208:211], v[16:31]
	ds_read_b128 v[136:139], v175 offset:46144
	v_mfma_f32_32x32x16_bf16 v[0:15], v[204:207], v[212:215], v[0:15]
	ds_read_b128 v[140:143], v175 offset:50752
	s_waitcnt lgkmcnt(0)
	v_mfma_f32_32x32x16_bf16 v[112:127], v[128:131], v[144:147], v[112:127]
	v_mfma_f32_32x32x16_bf16 v[96:111], v[128:131], v[148:151], v[96:111]
	ds_read_b128 v[208:211], v254 offset:36960
	v_mfma_f32_32x32x16_bf16 v[80:95], v[132:135], v[144:147], v[80:95]
	ds_read_b128 v[212:215], v254 offset:41568
	v_mfma_f32_32x32x16_bf16 v[64:79], v[132:135], v[148:151], v[64:79]
	ds_read_b128 v[192:195], v175 offset:36960
	v_mfma_f32_32x32x16_bf16 v[48:63], v[136:139], v[144:147], v[48:63]
	v_mfma_f32_32x32x16_bf16 v[32:47], v[136:139], v[148:151], v[32:47]
	ds_read_b128 v[196:199], v175 offset:41568
	v_mfma_f32_32x32x16_bf16 v[16:31], v[140:143], v[144:147], v[16:31]
	ds_read_b128 v[200:203], v175 offset:46176
	v_mfma_f32_32x32x16_bf16 v[0:15], v[140:143], v[148:151], v[0:15]
	ds_read_b128 v[204:207], v175 offset:50784
	s_waitcnt lgkmcnt(0)
	s_barrier
	ds_read_b128 v[144:147], v254 offset:0
	ds_read_b128 v[148:151], v254 offset:4608
	ds_read_b128 v[128:131], v175 offset:0
	ds_read_b128 v[132:135], v175 offset:4608
	ds_read_b128 v[136:139], v175 offset:9216
	ds_read_b128 v[140:143], v175 offset:13824
	v_mfma_f32_32x32x16_bf16 v[112:127], v[192:195], v[208:211], v[112:127]
	s_waitcnt vmcnt(0)
	v_mfma_f32_32x32x16_bf16 v[96:111], v[192:195], v[212:215], v[96:111]
	ds_write_b128 v170, v[162:165] offset:36864
	v_mfma_f32_32x32x16_bf16 v[80:95], v[196:199], v[208:211], v[80:95]
	ds_write_b128 v170, v[166:169] offset:46080
	v_mfma_f32_32x32x16_bf16 v[64:79], v[196:199], v[212:215], v[64:79]
	ds_write_b128 v170, v[176:179] offset:55296
	v_mfma_f32_32x32x16_bf16 v[48:63], v[200:203], v[208:211], v[48:63]
	ds_write_b128 v170, v[180:183] offset:64512
	v_mfma_f32_32x32x16_bf16 v[32:47], v[200:203], v[212:215], v[32:47]
	ds_write_b128 v171, v[184:187] offset:36864
	v_mfma_f32_32x32x16_bf16 v[16:31], v[204:207], v[208:211], v[16:31]
	ds_write_b128 v171, v[242:245] offset:46080
	v_mfma_f32_32x32x16_bf16 v[0:15], v[204:207], v[212:215], v[0:15]
	ds_write_b128 v171, v[246:249] offset:55296
	ds_write_b128 v171, v[250:253] offset:64512
	s_waitcnt lgkmcnt(8)
	v_mfma_f32_32x32x16_bf16 v[112:127], v[128:131], v[144:147], v[112:127]
	v_mfma_f32_32x32x16_bf16 v[96:111], v[128:131], v[148:151], v[96:111]
	ds_read_b128 v[208:211], v254 offset:32
	v_mfma_f32_32x32x16_bf16 v[80:95], v[132:135], v[144:147], v[80:95]
	ds_read_b128 v[212:215], v254 offset:4640
	v_mfma_f32_32x32x16_bf16 v[64:79], v[132:135], v[148:151], v[64:79]
	ds_read_b128 v[192:195], v175 offset:32
	v_mfma_f32_32x32x16_bf16 v[48:63], v[136:139], v[144:147], v[48:63]
	v_mfma_f32_32x32x16_bf16 v[32:47], v[136:139], v[148:151], v[32:47]
	ds_read_b128 v[196:199], v175 offset:4640
	v_mfma_f32_32x32x16_bf16 v[16:31], v[140:143], v[144:147], v[16:31]
	ds_read_b128 v[200:203], v175 offset:9248
	v_mfma_f32_32x32x16_bf16 v[0:15], v[140:143], v[148:151], v[0:15]
	ds_read_b128 v[204:207], v175 offset:13856
	s_waitcnt lgkmcnt(0)
	v_mfma_f32_32x32x16_bf16 v[112:127], v[192:195], v[208:211], v[112:127]
	v_mfma_f32_32x32x16_bf16 v[96:111], v[192:195], v[212:215], v[96:111]
	ds_read_b128 v[144:147], v254 offset:64
	v_mfma_f32_32x32x16_bf16 v[80:95], v[196:199], v[208:211], v[80:95]
	ds_read_b128 v[148:151], v254 offset:4672
	v_mfma_f32_32x32x16_bf16 v[64:79], v[196:199], v[212:215], v[64:79]
	ds_read_b128 v[128:131], v175 offset:64
	v_mfma_f32_32x32x16_bf16 v[48:63], v[200:203], v[208:211], v[48:63]
	v_mfma_f32_32x32x16_bf16 v[32:47], v[200:203], v[212:215], v[32:47]
	ds_read_b128 v[132:135], v175 offset:4672
	v_mfma_f32_32x32x16_bf16 v[16:31], v[204:207], v[208:211], v[16:31]
	ds_read_b128 v[136:139], v175 offset:9280
	v_mfma_f32_32x32x16_bf16 v[0:15], v[204:207], v[212:215], v[0:15]
	ds_read_b128 v[140:143], v175 offset:13888
	s_waitcnt lgkmcnt(0)
	v_mfma_f32_32x32x16_bf16 v[112:127], v[128:131], v[144:147], v[112:127]
	v_mfma_f32_32x32x16_bf16 v[96:111], v[128:131], v[148:151], v[96:111]
	ds_read_b128 v[208:211], v254 offset:96
	v_mfma_f32_32x32x16_bf16 v[80:95], v[132:135], v[144:147], v[80:95]
	ds_read_b128 v[212:215], v254 offset:4704
	v_mfma_f32_32x32x16_bf16 v[64:79], v[132:135], v[148:151], v[64:79]
	ds_read_b128 v[192:195], v175 offset:96
	v_mfma_f32_32x32x16_bf16 v[48:63], v[136:139], v[144:147], v[48:63]
	v_mfma_f32_32x32x16_bf16 v[32:47], v[136:139], v[148:151], v[32:47]
	ds_read_b128 v[196:199], v175 offset:4704
	v_mfma_f32_32x32x16_bf16 v[16:31], v[140:143], v[144:147], v[16:31]
	ds_read_b128 v[200:203], v175 offset:9312
	v_mfma_f32_32x32x16_bf16 v[0:15], v[140:143], v[148:151], v[0:15]
	ds_read_b128 v[204:207], v175 offset:13920
	s_waitcnt lgkmcnt(0)
	s_barrier
	ds_read_b128 v[144:147], v254 offset:36864
	ds_read_b128 v[148:151], v254 offset:41472
	ds_read_b128 v[128:131], v175 offset:36864
	ds_read_b128 v[132:135], v175 offset:41472
	ds_read_b128 v[136:139], v175 offset:46080
	ds_read_b128 v[140:143], v175 offset:50688
	v_mfma_f32_32x32x16_bf16 v[112:127], v[192:195], v[208:211], v[112:127]
	v_mfma_f32_32x32x16_bf16 v[96:111], v[192:195], v[212:215], v[96:111]
	v_mfma_f32_32x32x16_bf16 v[80:95], v[196:199], v[208:211], v[80:95]
	v_mfma_f32_32x32x16_bf16 v[64:79], v[196:199], v[212:215], v[64:79]
	v_mfma_f32_32x32x16_bf16 v[48:63], v[200:203], v[208:211], v[48:63]
	v_mfma_f32_32x32x16_bf16 v[32:47], v[200:203], v[212:215], v[32:47]
	v_mfma_f32_32x32x16_bf16 v[16:31], v[204:207], v[208:211], v[16:31]
	v_mfma_f32_32x32x16_bf16 v[0:15], v[204:207], v[212:215], v[0:15]
	s_waitcnt lgkmcnt(0)
	v_mfma_f32_32x32x16_bf16 v[112:127], v[128:131], v[144:147], v[112:127]
	v_mfma_f32_32x32x16_bf16 v[96:111], v[128:131], v[148:151], v[96:111]
	ds_read_b128 v[208:211], v254 offset:36896
	v_mfma_f32_32x32x16_bf16 v[80:95], v[132:135], v[144:147], v[80:95]
	ds_read_b128 v[212:215], v254 offset:41504
	v_mfma_f32_32x32x16_bf16 v[64:79], v[132:135], v[148:151], v[64:79]
	ds_read_b128 v[192:195], v175 offset:36896
	v_mfma_f32_32x32x16_bf16 v[48:63], v[136:139], v[144:147], v[48:63]
	v_mfma_f32_32x32x16_bf16 v[32:47], v[136:139], v[148:151], v[32:47]
	ds_read_b128 v[196:199], v175 offset:41504
	v_mfma_f32_32x32x16_bf16 v[16:31], v[140:143], v[144:147], v[16:31]
	ds_read_b128 v[200:203], v175 offset:46112
	v_mfma_f32_32x32x16_bf16 v[0:15], v[140:143], v[148:151], v[0:15]
	ds_read_b128 v[204:207], v175 offset:50720
	s_waitcnt lgkmcnt(0)
	v_mfma_f32_32x32x16_bf16 v[112:127], v[192:195], v[208:211], v[112:127]
	v_mfma_f32_32x32x16_bf16 v[96:111], v[192:195], v[212:215], v[96:111]
	ds_read_b128 v[144:147], v254 offset:36928
	v_mfma_f32_32x32x16_bf16 v[80:95], v[196:199], v[208:211], v[80:95]
	ds_read_b128 v[148:151], v254 offset:41536
	v_mfma_f32_32x32x16_bf16 v[64:79], v[196:199], v[212:215], v[64:79]
	ds_read_b128 v[128:131], v175 offset:36928
	v_mfma_f32_32x32x16_bf16 v[48:63], v[200:203], v[208:211], v[48:63]
	v_mfma_f32_32x32x16_bf16 v[32:47], v[200:203], v[212:215], v[32:47]
	ds_read_b128 v[132:135], v175 offset:41536
	v_mfma_f32_32x32x16_bf16 v[16:31], v[204:207], v[208:211], v[16:31]
	ds_read_b128 v[136:139], v175 offset:46144
	v_mfma_f32_32x32x16_bf16 v[0:15], v[204:207], v[212:215], v[0:15]
	ds_read_b128 v[140:143], v175 offset:50752
	s_waitcnt lgkmcnt(0)
	v_mfma_f32_32x32x16_bf16 v[112:127], v[128:131], v[144:147], v[112:127]
	v_mfma_f32_32x32x16_bf16 v[96:111], v[128:131], v[148:151], v[96:111]
	ds_read_b128 v[208:211], v254 offset:36960
	v_mfma_f32_32x32x16_bf16 v[80:95], v[132:135], v[144:147], v[80:95]
	ds_read_b128 v[212:215], v254 offset:41568
	v_mfma_f32_32x32x16_bf16 v[64:79], v[132:135], v[148:151], v[64:79]
	ds_read_b128 v[192:195], v175 offset:36960
	v_mfma_f32_32x32x16_bf16 v[48:63], v[136:139], v[144:147], v[48:63]
	v_mfma_f32_32x32x16_bf16 v[32:47], v[136:139], v[148:151], v[32:47]
	ds_read_b128 v[196:199], v175 offset:41568
	v_mfma_f32_32x32x16_bf16 v[16:31], v[140:143], v[144:147], v[16:31]
	ds_read_b128 v[200:203], v175 offset:46176
	v_mfma_f32_32x32x16_bf16 v[0:15], v[140:143], v[148:151], v[0:15]
	ds_read_b128 v[204:207], v175 offset:50784
	s_waitcnt lgkmcnt(0)
	s_barrier
	v_mfma_f32_32x32x16_bf16 v[112:127], v[192:195], v[208:211], v[112:127]
	v_mfma_f32_32x32x16_bf16 v[96:111], v[192:195], v[212:215], v[96:111]
	v_mfma_f32_32x32x16_bf16 v[80:95], v[196:199], v[208:211], v[80:95]
	v_mfma_f32_32x32x16_bf16 v[64:79], v[196:199], v[212:215], v[64:79]
	v_mfma_f32_32x32x16_bf16 v[48:63], v[200:203], v[208:211], v[48:63]
	v_mfma_f32_32x32x16_bf16 v[32:47], v[200:203], v[212:215], v[32:47]
	v_mfma_f32_32x32x16_bf16 v[16:31], v[204:207], v[208:211], v[16:31]
	v_mfma_f32_32x32x16_bf16 v[0:15], v[204:207], v[212:215], v[0:15]
	s_nop 7
	s_nop 7
	s_mul_i32 s100, s64, 0x2700
	s_mul_hi_u32 s101, s64, 0x2700
	s_add_u32 s100, s100, 0xa224000
	s_addc_u32 s101, s101, 0
	s_add_u32 s96, s92, s100
	s_addc_u32 s97, s93, s101
	s_and_b32 s97, s97, 0xffff
	s_mov_b32 s98, 0x270000
	s_mov_b32 s99, 0x20000
	s_movk_i32 s46, 0x7fff
	v_and_b32_e32 v132, 31, v190
	v_bfe_u32 v133, v190, 5, 1
	v_bfe_u32 v134, v190, 6, 2
	v_bfe_u32 v135, v190, 8, 1
	v_lshl_add_u32 v132, v134, 6, v132
	v_add_u32_e32 v132, s82, v132
	v_cmp_gt_u32_e32 vcc, 0x1380, v132
	s_mov_b64 s[74:75], vcc
	v_add_u32_e32 v136, 32, v132
	v_cmp_gt_u32_e32 vcc, 0x1380, v136
	s_mov_b64 s[76:77], vcc
	v_lshlrev_b32_e32 v132, 1, v132
	v_lshlrev_b32_e32 v135, 7, v135
	v_lshl_add_u32 v135, v133, 2, v135
	s_mov_b32 s47, 0x2700
	v_mul_lo_u32 v135, s47, v135
	v_add_u32_e32 v128, v135, v132
	v_add_u32_e32 v129, 0x2700, v128
	v_add_u32_e32 v130, 0x4e00, v128
	v_add_u32_e32 v131, 0x7500, v128
	s_mov_b64 exec, s[74:75]
	s_cbranch_execz .Lgskip_0_0
	v_bfe_u32 v136, v112, 16, 1
	v_bfe_u32 v137, v113, 16, 1
	v_bfe_u32 v138, v114, 16, 1
	v_bfe_u32 v139, v115, 16, 1
	v_add3_u32 v112, v112, v136, s46
	v_add3_u32 v113, v113, v137, s46
	v_add3_u32 v114, v114, v138, s46
	v_add3_u32 v115, v115, v139, s46
	s_mov_b32 s101, 0x0
	buffer_store_short_d16_hi v112, v128, s[96:99], s101 offen
	buffer_store_short_d16_hi v113, v129, s[96:99], s101 offen
	buffer_store_short_d16_hi v114, v130, s[96:99], s101 offen
	buffer_store_short_d16_hi v115, v131, s[96:99], s101 offen
	v_bfe_u32 v136, v116, 16, 1
	v_bfe_u32 v137, v117, 16, 1
	v_bfe_u32 v138, v118, 16, 1
	v_bfe_u32 v139, v119, 16, 1
	v_add3_u32 v116, v116, v136, s46
	v_add3_u32 v117, v117, v137, s46
	v_add3_u32 v118, v118, v138, s46
	v_add3_u32 v119, v119, v139, s46
	s_mov_b32 s101, 0x13800
	buffer_store_short_d16_hi v116, v128, s[96:99], s101 offen
	buffer_store_short_d16_hi v117, v129, s[96:99], s101 offen
	buffer_store_short_d16_hi v118, v130, s[96:99], s101 offen
	buffer_store_short_d16_hi v119, v131, s[96:99], s101 offen
	v_bfe_u32 v136, v120, 16, 1
	v_bfe_u32 v137, v121, 16, 1
	v_bfe_u32 v138, v122, 16, 1
	v_bfe_u32 v139, v123, 16, 1
	v_add3_u32 v120, v120, v136, s46
	v_add3_u32 v121, v121, v137, s46
	v_add3_u32 v122, v122, v138, s46
	v_add3_u32 v123, v123, v139, s46
	s_mov_b32 s101, 0x27000
	buffer_store_short_d16_hi v120, v128, s[96:99], s101 offen
	buffer_store_short_d16_hi v121, v129, s[96:99], s101 offen
	buffer_store_short_d16_hi v122, v130, s[96:99], s101 offen
	buffer_store_short_d16_hi v123, v131, s[96:99], s101 offen
	v_bfe_u32 v136, v124, 16, 1
	v_bfe_u32 v137, v125, 16, 1
	v_bfe_u32 v138, v126, 16, 1
	v_bfe_u32 v139, v127, 16, 1
	v_add3_u32 v124, v124, v136, s46
	v_add3_u32 v125, v125, v137, s46
	v_add3_u32 v126, v126, v138, s46
	v_add3_u32 v127, v127, v139, s46
	s_mov_b32 s101, 0x3a800
	buffer_store_short_d16_hi v124, v128, s[96:99], s101 offen
	buffer_store_short_d16_hi v125, v129, s[96:99], s101 offen
	buffer_store_short_d16_hi v126, v130, s[96:99], s101 offen
	buffer_store_short_d16_hi v127, v131, s[96:99], s101 offen
.Lgskip_0_0:
	s_mov_b64 exec, -1
	s_mov_b64 exec, s[76:77]
	s_cbranch_execz .Lgskip_0_1
	v_bfe_u32 v136, v96, 16, 1
	v_bfe_u32 v137, v97, 16, 1
	v_bfe_u32 v138, v98, 16, 1
	v_bfe_u32 v139, v99, 16, 1
	v_add3_u32 v96, v96, v136, s46
	v_add3_u32 v97, v97, v137, s46
	v_add3_u32 v98, v98, v138, s46
	v_add3_u32 v99, v99, v139, s46
	s_mov_b32 s101, 0x0
	buffer_store_short_d16_hi v96, v128, s[96:99], s101 offen offset:64
	buffer_store_short_d16_hi v97, v129, s[96:99], s101 offen offset:64
	buffer_store_short_d16_hi v98, v130, s[96:99], s101 offen offset:64
	buffer_store_short_d16_hi v99, v131, s[96:99], s101 offen offset:64
	v_bfe_u32 v136, v100, 16, 1
	v_bfe_u32 v137, v101, 16, 1
	v_bfe_u32 v138, v102, 16, 1
	v_bfe_u32 v139, v103, 16, 1
	v_add3_u32 v100, v100, v136, s46
	v_add3_u32 v101, v101, v137, s46
	v_add3_u32 v102, v102, v138, s46
	v_add3_u32 v103, v103, v139, s46
	s_mov_b32 s101, 0x13800
	buffer_store_short_d16_hi v100, v128, s[96:99], s101 offen offset:64
	buffer_store_short_d16_hi v101, v129, s[96:99], s101 offen offset:64
	buffer_store_short_d16_hi v102, v130, s[96:99], s101 offen offset:64
	buffer_store_short_d16_hi v103, v131, s[96:99], s101 offen offset:64
	v_bfe_u32 v136, v104, 16, 1
	v_bfe_u32 v137, v105, 16, 1
	v_bfe_u32 v138, v106, 16, 1
	v_bfe_u32 v139, v107, 16, 1
	v_add3_u32 v104, v104, v136, s46
	v_add3_u32 v105, v105, v137, s46
	v_add3_u32 v106, v106, v138, s46
	v_add3_u32 v107, v107, v139, s46
	s_mov_b32 s101, 0x27000
	buffer_store_short_d16_hi v104, v128, s[96:99], s101 offen offset:64
	buffer_store_short_d16_hi v105, v129, s[96:99], s101 offen offset:64
	buffer_store_short_d16_hi v106, v130, s[96:99], s101 offen offset:64
	buffer_store_short_d16_hi v107, v131, s[96:99], s101 offen offset:64
	v_bfe_u32 v136, v108, 16, 1
	v_bfe_u32 v137, v109, 16, 1
	v_bfe_u32 v138, v110, 16, 1
	v_bfe_u32 v139, v111, 16, 1
	v_add3_u32 v108, v108, v136, s46
	v_add3_u32 v109, v109, v137, s46
	v_add3_u32 v110, v110, v138, s46
	v_add3_u32 v111, v111, v139, s46
	s_mov_b32 s101, 0x3a800
	buffer_store_short_d16_hi v108, v128, s[96:99], s101 offen offset:64
	buffer_store_short_d16_hi v109, v129, s[96:99], s101 offen offset:64
	buffer_store_short_d16_hi v110, v130, s[96:99], s101 offen offset:64
	buffer_store_short_d16_hi v111, v131, s[96:99], s101 offen offset:64
.Lgskip_0_1:
	s_mov_b64 exec, -1
	s_mov_b64 exec, s[74:75]
	s_cbranch_execz .Lgskip_1_0
	v_bfe_u32 v136, v80, 16, 1
	v_bfe_u32 v137, v81, 16, 1
	v_bfe_u32 v138, v82, 16, 1
	v_bfe_u32 v139, v83, 16, 1
	v_add3_u32 v80, v80, v136, s46
	v_add3_u32 v81, v81, v137, s46
	v_add3_u32 v82, v82, v138, s46
	v_add3_u32 v83, v83, v139, s46
	s_mov_b32 s101, 0x4e000
	buffer_store_short_d16_hi v80, v128, s[96:99], s101 offen
	buffer_store_short_d16_hi v81, v129, s[96:99], s101 offen
	buffer_store_short_d16_hi v82, v130, s[96:99], s101 offen
	buffer_store_short_d16_hi v83, v131, s[96:99], s101 offen
	v_bfe_u32 v136, v84, 16, 1
	v_bfe_u32 v137, v85, 16, 1
	v_bfe_u32 v138, v86, 16, 1
	v_bfe_u32 v139, v87, 16, 1
	v_add3_u32 v84, v84, v136, s46
	v_add3_u32 v85, v85, v137, s46
	v_add3_u32 v86, v86, v138, s46
	v_add3_u32 v87, v87, v139, s46
	s_mov_b32 s101, 0x61800
	buffer_store_short_d16_hi v84, v128, s[96:99], s101 offen
	buffer_store_short_d16_hi v85, v129, s[96:99], s101 offen
	buffer_store_short_d16_hi v86, v130, s[96:99], s101 offen
	buffer_store_short_d16_hi v87, v131, s[96:99], s101 offen
	v_bfe_u32 v136, v88, 16, 1
	v_bfe_u32 v137, v89, 16, 1
	v_bfe_u32 v138, v90, 16, 1
	v_bfe_u32 v139, v91, 16, 1
	v_add3_u32 v88, v88, v136, s46
	v_add3_u32 v89, v89, v137, s46
	v_add3_u32 v90, v90, v138, s46
	v_add3_u32 v91, v91, v139, s46
	s_mov_b32 s101, 0x75000
	buffer_store_short_d16_hi v88, v128, s[96:99], s101 offen
	buffer_store_short_d16_hi v89, v129, s[96:99], s101 offen
	buffer_store_short_d16_hi v90, v130, s[96:99], s101 offen
	buffer_store_short_d16_hi v91, v131, s[96:99], s101 offen
	v_bfe_u32 v136, v92, 16, 1
	v_bfe_u32 v137, v93, 16, 1
	v_bfe_u32 v138, v94, 16, 1
	v_bfe_u32 v139, v95, 16, 1
	v_add3_u32 v92, v92, v136, s46
	v_add3_u32 v93, v93, v137, s46
	v_add3_u32 v94, v94, v138, s46
	v_add3_u32 v95, v95, v139, s46
	s_mov_b32 s101, 0x88800
	buffer_store_short_d16_hi v92, v128, s[96:99], s101 offen
	buffer_store_short_d16_hi v93, v129, s[96:99], s101 offen
	buffer_store_short_d16_hi v94, v130, s[96:99], s101 offen
	buffer_store_short_d16_hi v95, v131, s[96:99], s101 offen
.Lgskip_1_0:
	s_mov_b64 exec, -1
	s_mov_b64 exec, s[76:77]
	s_cbranch_execz .Lgskip_1_1
	v_bfe_u32 v136, v64, 16, 1
	v_bfe_u32 v137, v65, 16, 1
	v_bfe_u32 v138, v66, 16, 1
	v_bfe_u32 v139, v67, 16, 1
	v_add3_u32 v64, v64, v136, s46
	v_add3_u32 v65, v65, v137, s46
	v_add3_u32 v66, v66, v138, s46
	v_add3_u32 v67, v67, v139, s46
	s_mov_b32 s101, 0x4e000
	buffer_store_short_d16_hi v64, v128, s[96:99], s101 offen offset:64
	buffer_store_short_d16_hi v65, v129, s[96:99], s101 offen offset:64
	buffer_store_short_d16_hi v66, v130, s[96:99], s101 offen offset:64
	buffer_store_short_d16_hi v67, v131, s[96:99], s101 offen offset:64
	v_bfe_u32 v136, v68, 16, 1
	v_bfe_u32 v137, v69, 16, 1
	v_bfe_u32 v138, v70, 16, 1
	v_bfe_u32 v139, v71, 16, 1
	v_add3_u32 v68, v68, v136, s46
	v_add3_u32 v69, v69, v137, s46
	v_add3_u32 v70, v70, v138, s46
	v_add3_u32 v71, v71, v139, s46
	s_mov_b32 s101, 0x61800
	buffer_store_short_d16_hi v68, v128, s[96:99], s101 offen offset:64
	buffer_store_short_d16_hi v69, v129, s[96:99], s101 offen offset:64
	buffer_store_short_d16_hi v70, v130, s[96:99], s101 offen offset:64
	buffer_store_short_d16_hi v71, v131, s[96:99], s101 offen offset:64
	v_bfe_u32 v136, v72, 16, 1
	v_bfe_u32 v137, v73, 16, 1
	v_bfe_u32 v138, v74, 16, 1
	v_bfe_u32 v139, v75, 16, 1
	v_add3_u32 v72, v72, v136, s46
	v_add3_u32 v73, v73, v137, s46
	v_add3_u32 v74, v74, v138, s46
	v_add3_u32 v75, v75, v139, s46
	s_mov_b32 s101, 0x75000
	buffer_store_short_d16_hi v72, v128, s[96:99], s101 offen offset:64
	buffer_store_short_d16_hi v73, v129, s[96:99], s101 offen offset:64
	buffer_store_short_d16_hi v74, v130, s[96:99], s101 offen offset:64
	buffer_store_short_d16_hi v75, v131, s[96:99], s101 offen offset:64
	v_bfe_u32 v136, v76, 16, 1
	v_bfe_u32 v137, v77, 16, 1
	v_bfe_u32 v138, v78, 16, 1
	v_bfe_u32 v139, v79, 16, 1
	v_add3_u32 v76, v76, v136, s46
	v_add3_u32 v77, v77, v137, s46
	v_add3_u32 v78, v78, v138, s46
	v_add3_u32 v79, v79, v139, s46
	s_mov_b32 s101, 0x88800
	buffer_store_short_d16_hi v76, v128, s[96:99], s101 offen offset:64
	buffer_store_short_d16_hi v77, v129, s[96:99], s101 offen offset:64
	buffer_store_short_d16_hi v78, v130, s[96:99], s101 offen offset:64
	buffer_store_short_d16_hi v79, v131, s[96:99], s101 offen offset:64
.Lgskip_1_1:
	s_mov_b64 exec, -1
	s_mov_b64 exec, s[74:75]
	s_cbranch_execz .Lgskip_2_0
	v_bfe_u32 v136, v48, 16, 1
	v_bfe_u32 v137, v49, 16, 1
	v_bfe_u32 v138, v50, 16, 1
	v_bfe_u32 v139, v51, 16, 1
	v_add3_u32 v48, v48, v136, s46
	v_add3_u32 v49, v49, v137, s46
	v_add3_u32 v50, v50, v138, s46
	v_add3_u32 v51, v51, v139, s46
	s_mov_b32 s101, 0x9c000
	buffer_store_short_d16_hi v48, v128, s[96:99], s101 offen
	buffer_store_short_d16_hi v49, v129, s[96:99], s101 offen
	buffer_store_short_d16_hi v50, v130, s[96:99], s101 offen
	buffer_store_short_d16_hi v51, v131, s[96:99], s101 offen
	v_bfe_u32 v136, v52, 16, 1
	v_bfe_u32 v137, v53, 16, 1
	v_bfe_u32 v138, v54, 16, 1
	v_bfe_u32 v139, v55, 16, 1
	v_add3_u32 v52, v52, v136, s46
	v_add3_u32 v53, v53, v137, s46
	v_add3_u32 v54, v54, v138, s46
	v_add3_u32 v55, v55, v139, s46
	s_mov_b32 s101, 0xaf800
	buffer_store_short_d16_hi v52, v128, s[96:99], s101 offen
	buffer_store_short_d16_hi v53, v129, s[96:99], s101 offen
	buffer_store_short_d16_hi v54, v130, s[96:99], s101 offen
	buffer_store_short_d16_hi v55, v131, s[96:99], s101 offen
	v_bfe_u32 v136, v56, 16, 1
	v_bfe_u32 v137, v57, 16, 1
	v_bfe_u32 v138, v58, 16, 1
	v_bfe_u32 v139, v59, 16, 1
	v_add3_u32 v56, v56, v136, s46
	v_add3_u32 v57, v57, v137, s46
	v_add3_u32 v58, v58, v138, s46
	v_add3_u32 v59, v59, v139, s46
	s_mov_b32 s101, 0xc3000
	buffer_store_short_d16_hi v56, v128, s[96:99], s101 offen
	buffer_store_short_d16_hi v57, v129, s[96:99], s101 offen
	buffer_store_short_d16_hi v58, v130, s[96:99], s101 offen
	buffer_store_short_d16_hi v59, v131, s[96:99], s101 offen
	v_bfe_u32 v136, v60, 16, 1
	v_bfe_u32 v137, v61, 16, 1
	v_bfe_u32 v138, v62, 16, 1
	v_bfe_u32 v139, v63, 16, 1
	v_add3_u32 v60, v60, v136, s46
	v_add3_u32 v61, v61, v137, s46
	v_add3_u32 v62, v62, v138, s46
	v_add3_u32 v63, v63, v139, s46
	s_mov_b32 s101, 0xd6800
	buffer_store_short_d16_hi v60, v128, s[96:99], s101 offen
	buffer_store_short_d16_hi v61, v129, s[96:99], s101 offen
	buffer_store_short_d16_hi v62, v130, s[96:99], s101 offen
	buffer_store_short_d16_hi v63, v131, s[96:99], s101 offen
.Lgskip_2_0:
	s_mov_b64 exec, -1
	s_mov_b64 exec, s[76:77]
	s_cbranch_execz .Lgskip_2_1
	v_bfe_u32 v136, v32, 16, 1
	v_bfe_u32 v137, v33, 16, 1
	v_bfe_u32 v138, v34, 16, 1
	v_bfe_u32 v139, v35, 16, 1
	v_add3_u32 v32, v32, v136, s46
	v_add3_u32 v33, v33, v137, s46
	v_add3_u32 v34, v34, v138, s46
	v_add3_u32 v35, v35, v139, s46
	s_mov_b32 s101, 0x9c000
	buffer_store_short_d16_hi v32, v128, s[96:99], s101 offen offset:64
	buffer_store_short_d16_hi v33, v129, s[96:99], s101 offen offset:64
	buffer_store_short_d16_hi v34, v130, s[96:99], s101 offen offset:64
	buffer_store_short_d16_hi v35, v131, s[96:99], s101 offen offset:64
	v_bfe_u32 v136, v36, 16, 1
	v_bfe_u32 v137, v37, 16, 1
	v_bfe_u32 v138, v38, 16, 1
	v_bfe_u32 v139, v39, 16, 1
	v_add3_u32 v36, v36, v136, s46
	v_add3_u32 v37, v37, v137, s46
	v_add3_u32 v38, v38, v138, s46
	v_add3_u32 v39, v39, v139, s46
	s_mov_b32 s101, 0xaf800
	buffer_store_short_d16_hi v36, v128, s[96:99], s101 offen offset:64
	buffer_store_short_d16_hi v37, v129, s[96:99], s101 offen offset:64
	buffer_store_short_d16_hi v38, v130, s[96:99], s101 offen offset:64
	buffer_store_short_d16_hi v39, v131, s[96:99], s101 offen offset:64
	v_bfe_u32 v136, v40, 16, 1
	v_bfe_u32 v137, v41, 16, 1
	v_bfe_u32 v138, v42, 16, 1
	v_bfe_u32 v139, v43, 16, 1
	v_add3_u32 v40, v40, v136, s46
	v_add3_u32 v41, v41, v137, s46
	v_add3_u32 v42, v42, v138, s46
	v_add3_u32 v43, v43, v139, s46
	s_mov_b32 s101, 0xc3000
	buffer_store_short_d16_hi v40, v128, s[96:99], s101 offen offset:64
	buffer_store_short_d16_hi v41, v129, s[96:99], s101 offen offset:64
	buffer_store_short_d16_hi v42, v130, s[96:99], s101 offen offset:64
	buffer_store_short_d16_hi v43, v131, s[96:99], s101 offen offset:64
	v_bfe_u32 v136, v44, 16, 1
	v_bfe_u32 v137, v45, 16, 1
	v_bfe_u32 v138, v46, 16, 1
	v_bfe_u32 v139, v47, 16, 1
	v_add3_u32 v44, v44, v136, s46
	v_add3_u32 v45, v45, v137, s46
	v_add3_u32 v46, v46, v138, s46
	v_add3_u32 v47, v47, v139, s46
	s_mov_b32 s101, 0xd6800
	buffer_store_short_d16_hi v44, v128, s[96:99], s101 offen offset:64
	buffer_store_short_d16_hi v45, v129, s[96:99], s101 offen offset:64
	buffer_store_short_d16_hi v46, v130, s[96:99], s101 offen offset:64
	buffer_store_short_d16_hi v47, v131, s[96:99], s101 offen offset:64
.Lgskip_2_1:
	s_mov_b64 exec, -1
	s_mov_b64 exec, s[74:75]
	s_cbranch_execz .Lgskip_3_0
	v_bfe_u32 v136, v16, 16, 1
	v_bfe_u32 v137, v17, 16, 1
	v_bfe_u32 v138, v18, 16, 1
	v_bfe_u32 v139, v19, 16, 1
	v_add3_u32 v16, v16, v136, s46
	v_add3_u32 v17, v17, v137, s46
	v_add3_u32 v18, v18, v138, s46
	v_add3_u32 v19, v19, v139, s46
	s_mov_b32 s101, 0xea000
	buffer_store_short_d16_hi v16, v128, s[96:99], s101 offen
	buffer_store_short_d16_hi v17, v129, s[96:99], s101 offen
	buffer_store_short_d16_hi v18, v130, s[96:99], s101 offen
	buffer_store_short_d16_hi v19, v131, s[96:99], s101 offen
	v_bfe_u32 v136, v20, 16, 1
	v_bfe_u32 v137, v21, 16, 1
	v_bfe_u32 v138, v22, 16, 1
	v_bfe_u32 v139, v23, 16, 1
	v_add3_u32 v20, v20, v136, s46
	v_add3_u32 v21, v21, v137, s46
	v_add3_u32 v22, v22, v138, s46
	v_add3_u32 v23, v23, v139, s46
	s_mov_b32 s101, 0xfd800
	buffer_store_short_d16_hi v20, v128, s[96:99], s101 offen
	buffer_store_short_d16_hi v21, v129, s[96:99], s101 offen
	buffer_store_short_d16_hi v22, v130, s[96:99], s101 offen
	buffer_store_short_d16_hi v23, v131, s[96:99], s101 offen
	v_bfe_u32 v136, v24, 16, 1
	v_bfe_u32 v137, v25, 16, 1
	v_bfe_u32 v138, v26, 16, 1
	v_bfe_u32 v139, v27, 16, 1
	v_add3_u32 v24, v24, v136, s46
	v_add3_u32 v25, v25, v137, s46
	v_add3_u32 v26, v26, v138, s46
	v_add3_u32 v27, v27, v139, s46
	s_mov_b32 s101, 0x111000
	buffer_store_short_d16_hi v24, v128, s[96:99], s101 offen
	buffer_store_short_d16_hi v25, v129, s[96:99], s101 offen
	buffer_store_short_d16_hi v26, v130, s[96:99], s101 offen
	buffer_store_short_d16_hi v27, v131, s[96:99], s101 offen
	v_bfe_u32 v136, v28, 16, 1
	v_bfe_u32 v137, v29, 16, 1
	v_bfe_u32 v138, v30, 16, 1
	v_bfe_u32 v139, v31, 16, 1
	v_add3_u32 v28, v28, v136, s46
	v_add3_u32 v29, v29, v137, s46
	v_add3_u32 v30, v30, v138, s46
	v_add3_u32 v31, v31, v139, s46
	s_mov_b32 s101, 0x124800
	buffer_store_short_d16_hi v28, v128, s[96:99], s101 offen
	buffer_store_short_d16_hi v29, v129, s[96:99], s101 offen
	buffer_store_short_d16_hi v30, v130, s[96:99], s101 offen
	buffer_store_short_d16_hi v31, v131, s[96:99], s101 offen
.Lgskip_3_0:
	s_mov_b64 exec, -1
	s_mov_b64 exec, s[76:77]
	s_cbranch_execz .Lgskip_3_1
	v_bfe_u32 v136, v0, 16, 1
	v_bfe_u32 v137, v1, 16, 1
	v_bfe_u32 v138, v2, 16, 1
	v_bfe_u32 v139, v3, 16, 1
	v_add3_u32 v0, v0, v136, s46
	v_add3_u32 v1, v1, v137, s46
	v_add3_u32 v2, v2, v138, s46
	v_add3_u32 v3, v3, v139, s46
	s_mov_b32 s101, 0xea000
	buffer_store_short_d16_hi v0, v128, s[96:99], s101 offen offset:64
	buffer_store_short_d16_hi v1, v129, s[96:99], s101 offen offset:64
	buffer_store_short_d16_hi v2, v130, s[96:99], s101 offen offset:64
	buffer_store_short_d16_hi v3, v131, s[96:99], s101 offen offset:64
	v_bfe_u32 v136, v4, 16, 1
	v_bfe_u32 v137, v5, 16, 1
	v_bfe_u32 v138, v6, 16, 1
	v_bfe_u32 v139, v7, 16, 1
	v_add3_u32 v4, v4, v136, s46
	v_add3_u32 v5, v5, v137, s46
	v_add3_u32 v6, v6, v138, s46
	v_add3_u32 v7, v7, v139, s46
	s_mov_b32 s101, 0xfd800
	buffer_store_short_d16_hi v4, v128, s[96:99], s101 offen offset:64
	buffer_store_short_d16_hi v5, v129, s[96:99], s101 offen offset:64
	buffer_store_short_d16_hi v6, v130, s[96:99], s101 offen offset:64
	buffer_store_short_d16_hi v7, v131, s[96:99], s101 offen offset:64
	v_bfe_u32 v136, v8, 16, 1
	v_bfe_u32 v137, v9, 16, 1
	v_bfe_u32 v138, v10, 16, 1
	v_bfe_u32 v139, v11, 16, 1
	v_add3_u32 v8, v8, v136, s46
	v_add3_u32 v9, v9, v137, s46
	v_add3_u32 v10, v10, v138, s46
	v_add3_u32 v11, v11, v139, s46
	s_mov_b32 s101, 0x111000
	buffer_store_short_d16_hi v8, v128, s[96:99], s101 offen offset:64
	buffer_store_short_d16_hi v9, v129, s[96:99], s101 offen offset:64
	buffer_store_short_d16_hi v10, v130, s[96:99], s101 offen offset:64
	buffer_store_short_d16_hi v11, v131, s[96:99], s101 offen offset:64
	v_bfe_u32 v136, v12, 16, 1
	v_bfe_u32 v137, v13, 16, 1
	v_bfe_u32 v138, v14, 16, 1
	v_bfe_u32 v139, v15, 16, 1
	v_add3_u32 v12, v12, v136, s46
	v_add3_u32 v13, v13, v137, s46
	v_add3_u32 v14, v14, v138, s46
	v_add3_u32 v15, v15, v139, s46
	s_mov_b32 s101, 0x124800
	buffer_store_short_d16_hi v12, v128, s[96:99], s101 offen offset:64
	buffer_store_short_d16_hi v13, v129, s[96:99], s101 offen offset:64
	buffer_store_short_d16_hi v14, v130, s[96:99], s101 offen offset:64
	buffer_store_short_d16_hi v15, v131, s[96:99], s101 offen offset:64
.Lgskip_3_1:
	s_mov_b64 exec, -1
	s_add_i32 s36, s36, s94
	s_cmpk_lt_i32 s36, 0x500
	s_cbranch_scc1 .Lgin0_tile
	s_branch .LBB0_211

.LBB0_1641:
.Lgin1_tile:
	s_and_b32 s100, s39, 7
	s_bfe_u32 s101, s39, 0x50003
	s_lshr_b32 s82, s39, 8
	s_lshl_b32 s64, s82, 2
	s_and_b32 s82, s101, 3
	s_add_u32 s64, s64, s82
	s_lshl_b32 s82, s100, 3
	s_lshr_b32 s101, s101, 2
	s_add_u32 s82, s82, s101
	s_lshl_b32 s64, s64, 8
	s_lshl_b32 s82, s82, 8
	s_lshl_b32 s100, s64, 12
	s_add_u32 s100, s100, 0x1b80000
	s_add_u32 s48, s92, s100
	s_addc_u32 s49, s93, 0
	s_and_b32 s49, s49, 0xffff
	s_mov_b32 s50, 0x100000
	s_mov_b32 s51, 0x20000
	s_lshl_b32 s100, s82, 12
	s_add_u32 s100, s100, 0x6224000
	s_add_u32 s52, s92, s100
	s_addc_u32 s53, s93, 0
	s_and_b32 s53, s53, 0xffff
	s_sub_u32 s100, 0x4000, s82
	s_min_u32 s100, s100, 0x100
	s_lshl_b32 s54, s100, 12
	s_mov_b32 s55, 0x20000
	s_mov_b32 s46, 0x40000
	s_mov_b32 s47, 0x80000
	s_mov_b32 s58, 0xc0000
	v_lshrrev_b32_e32 v128, 3, v190
	v_and_b32_e32 v129, 7, v190
	v_lshlrev_b32_e32 v129, 4, v129
	v_lshl_add_u32 v160, v128, 12, v129
	v_mul_u32_u24_e32 v130, 0x90, v128
	v_add_u32_e32 v170, v130, v129
	v_add_u32_e32 v171, 0x12000, v170
	v_and_b32_e32 v131, 31, v190
	v_bfe_u32 v132, v190, 5, 1
	v_bfe_u32 v133, v190, 6, 2
	v_bfe_u32 v134, v190, 8, 1
	v_lshl_add_u32 v135, v134, 7, v131
	v_mul_u32_u24_e32 v135, 0x90, v135
	v_lshl_add_u32 v175, v132, 4, v135
	v_lshl_add_u32 v136, v133, 6, v131
	v_mul_u32_u24_e32 v136, 0x90, v136
	v_lshl_add_u32 v136, v132, 4, v136
	v_add_u32_e32 v254, 0x12000, v136
	v_mov_b32_e32 v0, 0
	v_mov_b32_e32 v1, 0
	v_mov_b32_e32 v2, 0
	v_mov_b32_e32 v3, 0
	v_mov_b32_e32 v4, 0
	v_mov_b32_e32 v5, 0
	v_mov_b32_e32 v6, 0
	v_mov_b32_e32 v7, 0
	v_mov_b32_e32 v8, 0
	v_mov_b32_e32 v9, 0
	v_mov_b32_e32 v10, 0
	v_mov_b32_e32 v11, 0
	v_mov_b32_e32 v12, 0
	v_mov_b32_e32 v13, 0
	v_mov_b32_e32 v14, 0
	v_mov_b32_e32 v15, 0
	v_mov_b32_e32 v16, 0
	v_mov_b32_e32 v17, 0
	v_mov_b32_e32 v18, 0
	v_mov_b32_e32 v19, 0
	v_mov_b32_e32 v20, 0
	v_mov_b32_e32 v21, 0
	v_mov_b32_e32 v22, 0
	v_mov_b32_e32 v23, 0
	v_mov_b32_e32 v24, 0
	v_mov_b32_e32 v25, 0
	v_mov_b32_e32 v26, 0
	v_mov_b32_e32 v27, 0
	v_mov_b32_e32 v28, 0
	v_mov_b32_e32 v29, 0
	v_mov_b32_e32 v30, 0
	v_mov_b32_e32 v31, 0
	v_mov_b32_e32 v32, 0
	v_mov_b32_e32 v33, 0
	v_mov_b32_e32 v34, 0
	v_mov_b32_e32 v35, 0
	v_mov_b32_e32 v36, 0
	v_mov_b32_e32 v37, 0
	v_mov_b32_e32 v38, 0
	v_mov_b32_e32 v39, 0
	v_mov_b32_e32 v40, 0
	v_mov_b32_e32 v41, 0
	v_mov_b32_e32 v42, 0
	v_mov_b32_e32 v43, 0
	v_mov_b32_e32 v44, 0
	v_mov_b32_e32 v45, 0
	v_mov_b32_e32 v46, 0
	v_mov_b32_e32 v47, 0
	v_mov_b32_e32 v48, 0
	v_mov_b32_e32 v49, 0
	v_mov_b32_e32 v50, 0
	v_mov_b32_e32 v51, 0
	v_mov_b32_e32 v52, 0
	v_mov_b32_e32 v53, 0
	v_mov_b32_e32 v54, 0
	v_mov_b32_e32 v55, 0
	v_mov_b32_e32 v56, 0
	v_mov_b32_e32 v57, 0
	v_mov_b32_e32 v58, 0
	v_mov_b32_e32 v59, 0
	v_mov_b32_e32 v60, 0
	v_mov_b32_e32 v61, 0
	v_mov_b32_e32 v62, 0
	v_mov_b32_e32 v63, 0
	v_mov_b32_e32 v64, 0
	v_mov_b32_e32 v65, 0
	v_mov_b32_e32 v66, 0
	v_mov_b32_e32 v67, 0
	v_mov_b32_e32 v68, 0
	v_mov_b32_e32 v69, 0
	v_mov_b32_e32 v70, 0
	v_mov_b32_e32 v71, 0
	v_mov_b32_e32 v72, 0
	v_mov_b32_e32 v73, 0
	v_mov_b32_e32 v74, 0
	v_mov_b32_e32 v75, 0
	v_mov_b32_e32 v76, 0
	v_mov_b32_e32 v77, 0
	v_mov_b32_e32 v78, 0
	v_mov_b32_e32 v79, 0
	v_mov_b32_e32 v80, 0
	v_mov_b32_e32 v81, 0
	v_mov_b32_e32 v82, 0
	v_mov_b32_e32 v83, 0
	v_mov_b32_e32 v84, 0
	v_mov_b32_e32 v85, 0
	v_mov_b32_e32 v86, 0
	v_mov_b32_e32 v87, 0
	v_mov_b32_e32 v88, 0
	v_mov_b32_e32 v89, 0
	v_mov_b32_e32 v90, 0
	v_mov_b32_e32 v91, 0
	v_mov_b32_e32 v92, 0
	v_mov_b32_e32 v93, 0
	v_mov_b32_e32 v94, 0
	v_mov_b32_e32 v95, 0
	v_mov_b32_e32 v96, 0
	v_mov_b32_e32 v97, 0
	v_mov_b32_e32 v98, 0
	v_mov_b32_e32 v99, 0
	v_mov_b32_e32 v100, 0
	v_mov_b32_e32 v101, 0
	v_mov_b32_e32 v102, 0
	v_mov_b32_e32 v103, 0
	v_mov_b32_e32 v104, 0
	v_mov_b32_e32 v105, 0
	v_mov_b32_e32 v106, 0
	v_mov_b32_e32 v107, 0
	v_mov_b32_e32 v108, 0
	v_mov_b32_e32 v109, 0
	v_mov_b32_e32 v110, 0
	v_mov_b32_e32 v111, 0
	v_mov_b32_e32 v112, 0
	v_mov_b32_e32 v113, 0
	v_mov_b32_e32 v114, 0
	v_mov_b32_e32 v115, 0
	v_mov_b32_e32 v116, 0
	v_mov_b32_e32 v117, 0
	v_mov_b32_e32 v118, 0
	v_mov_b32_e32 v119, 0
	v_mov_b32_e32 v120, 0
	v_mov_b32_e32 v121, 0
	v_mov_b32_e32 v122, 0
	v_mov_b32_e32 v123, 0
	v_mov_b32_e32 v124, 0
	v_mov_b32_e32 v125, 0
	v_mov_b32_e32 v126, 0
	v_mov_b32_e32 v127, 0
	v_mov_b32_e32 v192, 0
	v_mov_b32_e32 v193, 0
	v_mov_b32_e32 v194, 0
	v_mov_b32_e32 v195, 0
	v_mov_b32_e32 v196, 0
	v_mov_b32_e32 v197, 0
	v_mov_b32_e32 v198, 0
	v_mov_b32_e32 v199, 0
	v_mov_b32_e32 v200, 0
	v_mov_b32_e32 v201, 0
	v_mov_b32_e32 v202, 0
	v_mov_b32_e32 v203, 0
	v_mov_b32_e32 v204, 0
	v_mov_b32_e32 v205, 0
	v_mov_b32_e32 v206, 0
	v_mov_b32_e32 v207, 0
	v_mov_b32_e32 v208, 0
	v_mov_b32_e32 v209, 0
	v_mov_b32_e32 v210, 0
	v_mov_b32_e32 v211, 0
	v_mov_b32_e32 v212, 0
	v_mov_b32_e32 v213, 0
	v_mov_b32_e32 v214, 0
	v_mov_b32_e32 v215, 0
	v_mov_b32_e32 v188, 0
	v_mov_b32_e32 v189, 0
	buffer_load_dwordx4 v[216:219], v160, s[48:51], 0 offen
	buffer_load_dwordx4 v[220:223], v160, s[48:51], s46 offen
	buffer_load_dwordx4 v[224:227], v160, s[48:51], s47 offen
	buffer_load_dwordx4 v[228:231], v160, s[48:51], s58 offen
	buffer_load_dwordx4 v[232:235], v160, s[52:55], 0 offen
	buffer_load_dwordx4 v[236:239], v160, s[52:55], s46 offen
	buffer_load_dwordx4 v[152:155], v160, s[52:55], s47 offen
	buffer_load_dwordx4 v[156:159], v160, s[52:55], s58 offen
	v_add_u32_e32 v160, 0x80, v160
	buffer_load_dwordx4 v[162:165], v160, s[48:51], 0 offen
	buffer_load_dwordx4 v[166:169], v160, s[48:51], s46 offen
	buffer_load_dwordx4 v[176:179], v160, s[48:51], s47 offen
	buffer_load_dwordx4 v[180:183], v160, s[48:51], s58 offen
	buffer_load_dwordx4 v[184:187], v160, s[52:55], 0 offen
	buffer_load_dwordx4 v[242:245], v160, s[52:55], s46 offen
	buffer_load_dwordx4 v[246:249], v160, s[52:55], s47 offen
	buffer_load_dwordx4 v[250:253], v160, s[52:55], s58 offen
	v_add_u32_e32 v160, 0x80, v160
	s_waitcnt vmcnt(8)
	ds_write_b128 v170, v[216:219] offset:0
	ds_write_b128 v170, v[220:223] offset:9216
	ds_write_b128 v170, v[224:227] offset:18432
	ds_write_b128 v170, v[228:231] offset:27648
	ds_write_b128 v171, v[232:235] offset:0
	ds_write_b128 v171, v[236:239] offset:9216
	ds_write_b128 v171, v[152:155] offset:18432
	ds_write_b128 v171, v[156:159] offset:27648
	buffer_load_dwordx4 v[216:219], v160, s[48:51], 0 offen
	buffer_load_dwordx4 v[220:223], v160, s[48:51], s46 offen
	buffer_load_dwordx4 v[224:227], v160, s[48:51], s47 offen
	buffer_load_dwordx4 v[228:231], v160, s[48:51], s58 offen
	buffer_load_dwordx4 v[232:235], v160, s[52:55], 0 offen
	buffer_load_dwordx4 v[236:239], v160, s[52:55], s46 offen
	buffer_load_dwordx4 v[152:155], v160, s[52:55], s47 offen
	buffer_load_dwordx4 v[156:159], v160, s[52:55], s58 offen
	v_add_u32_e32 v160, 0x80, v160
	s_waitcnt lgkmcnt(0)
	s_barrier
	s_movk_i32 s59, 14
.Lgin1_loop:
	ds_read_b128 v[144:147], v254 offset:0
	ds_read_b128 v[148:151], v254 offset:4608
	ds_read_b128 v[128:131], v175 offset:0
	ds_read_b128 v[132:135], v175 offset:4608
	ds_read_b128 v[136:139], v175 offset:9216
	ds_read_b128 v[140:143], v175 offset:13824
	v_mfma_f32_32x32x16_bf16 v[112:127], v[192:195], v[208:211], v[112:127]
	s_waitcnt vmcnt(8)
	v_mfma_f32_32x32x16_bf16 v[96:111], v[192:195], v[212:215], v[96:111]
	ds_write_b128 v170, v[162:165] offset:36864
	v_mfma_f32_32x32x16_bf16 v[80:95], v[196:199], v[208:211], v[80:95]
	ds_write_b128 v170, v[166:169] offset:46080
	v_mfma_f32_32x32x16_bf16 v[64:79], v[196:199], v[212:215], v[64:79]
	ds_write_b128 v170, v[176:179] offset:55296
	v_mfma_f32_32x32x16_bf16 v[48:63], v[200:203], v[208:211], v[48:63]
	ds_write_b128 v170, v[180:183] offset:64512
	v_mfma_f32_32x32x16_bf16 v[32:47], v[200:203], v[212:215], v[32:47]
	ds_write_b128 v171, v[184:187] offset:36864
	v_mfma_f32_32x32x16_bf16 v[16:31], v[204:207], v[208:211], v[16:31]
	ds_write_b128 v171, v[242:245] offset:46080
	v_mfma_f32_32x32x16_bf16 v[0:15], v[204:207], v[212:215], v[0:15]
	ds_write_b128 v171, v[246:249] offset:55296
	ds_write_b128 v171, v[250:253] offset:64512
	s_waitcnt lgkmcnt(8)
	v_mfma_f32_32x32x16_bf16 v[112:127], v[128:131], v[144:147], v[112:127]
	ds_read_b128 v[208:211], v254 offset:32
	v_mfma_f32_32x32x16_bf16 v[96:111], v[128:131], v[148:151], v[96:111]
	ds_read_b128 v[212:215], v254 offset:4640
	ds_read_b128 v[192:195], v175 offset:32
	v_mfma_f32_32x32x16_bf16 v[80:95], v[132:135], v[144:147], v[80:95]
	ds_read_b128 v[196:199], v175 offset:4640
	ds_read_b128 v[200:203], v175 offset:9248
	v_mfma_f32_32x32x16_bf16 v[64:79], v[132:135], v[148:151], v[64:79]
	ds_read_b128 v[204:207], v175 offset:13856
	buffer_load_dwordx4 v[162:165], v160, s[48:51], 0 offen
	v_mfma_f32_32x32x16_bf16 v[48:63], v[136:139], v[144:147], v[48:63]
	buffer_load_dwordx4 v[166:169], v160, s[48:51], s46 offen
	buffer_load_dwordx4 v[176:179], v160, s[48:51], s47 offen
	v_mfma_f32_32x32x16_bf16 v[32:47], v[136:139], v[148:151], v[32:47]
	buffer_load_dwordx4 v[180:183], v160, s[48:51], s58 offen
	buffer_load_dwordx4 v[184:187], v160, s[52:55], 0 offen
	v_mfma_f32_32x32x16_bf16 v[16:31], v[140:143], v[144:147], v[16:31]
	buffer_load_dwordx4 v[242:245], v160, s[52:55], s46 offen
	buffer_load_dwordx4 v[246:249], v160, s[52:55], s47 offen
	v_mfma_f32_32x32x16_bf16 v[0:15], v[140:143], v[148:151], v[0:15]
	buffer_load_dwordx4 v[250:253], v160, s[52:55], s58 offen
	v_add_u32_e32 v160, 0x80, v160
	s_waitcnt lgkmcnt(0)
	v_mfma_f32_32x32x16_bf16 v[112:127], v[192:195], v[208:211], v[112:127]
	v_mfma_f32_32x32x16_bf16 v[96:111], v[192:195], v[212:215], v[96:111]
	ds_read_b128 v[144:147], v254 offset:64
	v_mfma_f32_32x32x16_bf16 v[80:95], v[196:199], v[208:211], v[80:95]
	ds_read_b128 v[148:151], v254 offset:4672
	v_mfma_f32_32x32x16_bf16 v[64:79], v[196:199], v[212:215], v[64:79]
	ds_read_b128 v[128:131], v175 offset:64
	v_mfma_f32_32x32x16_bf16 v[48:63], v[200:203], v[208:211], v[48:63]
	v_mfma_f32_32x32x16_bf16 v[32:47], v[200:203], v[212:215], v[32:47]
	ds_read_b128 v[132:135], v175 offset:4672
	v_mfma_f32_32x32x16_bf16 v[16:31], v[204:207], v[208:211], v[16:31]
	ds_read_b128 v[136:139], v175 offset:9280
	v_mfma_f32_32x32x16_bf16 v[0:15], v[204:207], v[212:215], v[0:15]
	ds_read_b128 v[140:143], v175 offset:13888
	s_waitcnt lgkmcnt(0)
	v_mfma_f32_32x32x16_bf16 v[112:127], v[128:131], v[144:147], v[112:127]
	v_mfma_f32_32x32x16_bf16 v[96:111], v[128:131], v[148:151], v[96:111]
	ds_read_b128 v[208:211], v254 offset:96
	v_mfma_f32_32x32x16_bf16 v[80:95], v[132:135], v[144:147], v[80:95]
	ds_read_b128 v[212:215], v254 offset:4704
	v_mfma_f32_32x32x16_bf16 v[64:79], v[132:135], v[148:151], v[64:79]
	ds_read_b128 v[192:195], v175 offset:96
	v_mfma_f32_32x32x16_bf16 v[48:63], v[136:139], v[144:147], v[48:63]
	v_mfma_f32_32x32x16_bf16 v[32:47], v[136:139], v[148:151], v[32:47]
	ds_read_b128 v[196:199], v175 offset:4704
	v_mfma_f32_32x32x16_bf16 v[16:31], v[140:143], v[144:147], v[16:31]
	ds_read_b128 v[200:203], v175 offset:9312
	v_mfma_f32_32x32x16_bf16 v[0:15], v[140:143], v[148:151], v[0:15]
	ds_read_b128 v[204:207], v175 offset:13920
	s_waitcnt lgkmcnt(0)
	s_barrier
	ds_read_b128 v[144:147], v254 offset:36864
	ds_read_b128 v[148:151], v254 offset:41472
	ds_read_b128 v[128:131], v175 offset:36864
	ds_read_b128 v[132:135], v175 offset:41472
	ds_read_b128 v[136:139], v175 offset:46080
	ds_read_b128 v[140:143], v175 offset:50688
	v_mfma_f32_32x32x16_bf16 v[112:127], v[192:195], v[208:211], v[112:127]
	s_waitcnt vmcnt(8)
	v_mfma_f32_32x32x16_bf16 v[96:111], v[192:195], v[212:215], v[96:111]
	ds_write_b128 v170, v[216:219] offset:0
	v_mfma_f32_32x32x16_bf16 v[80:95], v[196:199], v[208:211], v[80:95]
	ds_write_b128 v170, v[220:223] offset:9216
	v_mfma_f32_32x32x16_bf16 v[64:79], v[196:199], v[212:215], v[64:79]
	ds_write_b128 v170, v[224:227] offset:18432
	v_mfma_f32_32x32x16_bf16 v[48:63], v[200:203], v[208:211], v[48:63]
	ds_write_b128 v170, v[228:231] offset:27648
	v_mfma_f32_32x32x16_bf16 v[32:47], v[200:203], v[212:215], v[32:47]
	ds_write_b128 v171, v[232:235] offset:0
	v_mfma_f32_32x32x16_bf16 v[16:31], v[204:207], v[208:211], v[16:31]
	ds_write_b128 v171, v[236:239] offset:9216
	v_mfma_f32_32x32x16_bf16 v[0:15], v[204:207], v[212:215], v[0:15]
	ds_write_b128 v171, v[152:155] offset:18432
	ds_write_b128 v171, v[156:159] offset:27648
	s_waitcnt lgkmcnt(8)
	v_mfma_f32_32x32x16_bf16 v[112:127], v[128:131], v[144:147], v[112:127]
	ds_read_b128 v[208:211], v254 offset:36896
	v_mfma_f32_32x32x16_bf16 v[96:111], v[128:131], v[148:151], v[96:111]
	ds_read_b128 v[212:215], v254 offset:41504
	ds_read_b128 v[192:195], v175 offset:36896
	v_mfma_f32_32x32x16_bf16 v[80:95], v[132:135], v[144:147], v[80:95]
	ds_read_b128 v[196:199], v175 offset:41504
	ds_read_b128 v[200:203], v175 offset:46112
	v_mfma_f32_32x32x16_bf16 v[64:79], v[132:135], v[148:151], v[64:79]
	ds_read_b128 v[204:207], v175 offset:50720
	buffer_load_dwordx4 v[216:219], v160, s[48:51], 0 offen
	v_mfma_f32_32x32x16_bf16 v[48:63], v[136:139], v[144:147], v[48:63]
	buffer_load_dwordx4 v[220:223], v160, s[48:51], s46 offen
	buffer_load_dwordx4 v[224:227], v160, s[48:51], s47 offen
	v_mfma_f32_32x32x16_bf16 v[32:47], v[136:139], v[148:151], v[32:47]
	buffer_load_dwordx4 v[228:231], v160, s[48:51], s58 offen
	buffer_load_dwordx4 v[232:235], v160, s[52:55], 0 offen
	v_mfma_f32_32x32x16_bf16 v[16:31], v[140:143], v[144:147], v[16:31]
	buffer_load_dwordx4 v[236:239], v160, s[52:55], s46 offen
	buffer_load_dwordx4 v[152:155], v160, s[52:55], s47 offen
	v_mfma_f32_32x32x16_bf16 v[0:15], v[140:143], v[148:151], v[0:15]
	buffer_load_dwordx4 v[156:159], v160, s[52:55], s58 offen
	v_add_u32_e32 v160, 0x80, v160
	s_waitcnt lgkmcnt(0)
	v_mfma_f32_32x32x16_bf16 v[112:127], v[192:195], v[208:211], v[112:127]
	v_mfma_f32_32x32x16_bf16 v[96:111], v[192:195], v[212:215], v[96:111]
	ds_read_b128 v[144:147], v254 offset:36928
	v_mfma_f32_32x32x16_bf16 v[80:95], v[196:199], v[208:211], v[80:95]
	ds_read_b128 v[148:151], v254 offset:41536
	v_mfma_f32_32x32x16_bf16 v[64:79], v[196:199], v[212:215], v[64:79]
	ds_read_b128 v[128:131], v175 offset:36928
	v_mfma_f32_32x32x16_bf16 v[48:63], v[200:203], v[208:211], v[48:63]
	v_mfma_f32_32x32x16_bf16 v[32:47], v[200:203], v[212:215], v[32:47]
	ds_read_b128 v[132:135], v175 offset:41536
	v_mfma_f32_32x32x16_bf16 v[16:31], v[204:207], v[208:211], v[16:31]
	ds_read_b128 v[136:139], v175 offset:46144
	v_mfma_f32_32x32x16_bf16 v[0:15], v[204:207], v[212:215], v[0:15]
	ds_read_b128 v[140:143], v175 offset:50752
	s_waitcnt lgkmcnt(0)
	v_mfma_f32_32x32x16_bf16 v[112:127], v[128:131], v[144:147], v[112:127]
	v_mfma_f32_32x32x16_bf16 v[96:111], v[128:131], v[148:151], v[96:111]
	ds_read_b128 v[208:211], v254 offset:36960
	v_mfma_f32_32x32x16_bf16 v[80:95], v[132:135], v[144:147], v[80:95]
	ds_read_b128 v[212:215], v254 offset:41568
	v_mfma_f32_32x32x16_bf16 v[64:79], v[132:135], v[148:151], v[64:79]
	ds_read_b128 v[192:195], v175 offset:36960
	v_mfma_f32_32x32x16_bf16 v[48:63], v[136:139], v[144:147], v[48:63]
	v_mfma_f32_32x32x16_bf16 v[32:47], v[136:139], v[148:151], v[32:47]
	ds_read_b128 v[196:199], v175 offset:41568
	v_mfma_f32_32x32x16_bf16 v[16:31], v[140:143], v[144:147], v[16:31]
	ds_read_b128 v[200:203], v175 offset:46176
	v_mfma_f32_32x32x16_bf16 v[0:15], v[140:143], v[148:151], v[0:15]
	ds_read_b128 v[204:207], v175 offset:50784
	s_waitcnt lgkmcnt(0)
	s_barrier
	s_add_i32 s59, s59, -1
	s_cmp_lg_u32 s59, 0
	s_cbranch_scc1 .Lgin1_loop
	ds_read_b128 v[144:147], v254 offset:0
	ds_read_b128 v[148:151], v254 offset:4608
	ds_read_b128 v[128:131], v175 offset:0
	ds_read_b128 v[132:135], v175 offset:4608
	ds_read_b128 v[136:139], v175 offset:9216
	ds_read_b128 v[140:143], v175 offset:13824
	v_mfma_f32_32x32x16_bf16 v[112:127], v[192:195], v[208:211], v[112:127]
	s_waitcnt vmcnt(8)
	v_mfma_f32_32x32x16_bf16 v[96:111], v[192:195], v[212:215], v[96:111]
	ds_write_b128 v170, v[162:165] offset:36864
	v_mfma_f32_32x32x16_bf16 v[80:95], v[196:199], v[208:211], v[80:95]
	ds_write_b128 v170, v[166:169] offset:46080
	v_mfma_f32_32x32x16_bf16 v[64:79], v[196:199], v[212:215], v[64:79]
	ds_write_b128 v170, v[176:179] offset:55296
	v_mfma_f32_32x32x16_bf16 v[48:63], v[200:203], v[208:211], v[48:63]
	ds_write_b128 v170, v[180:183] offset:64512
	v_mfma_f32_32x32x16_bf16 v[32:47], v[200:203], v[212:215], v[32:47]
	ds_write_b128 v171, v[184:187] offset:36864
	v_mfma_f32_32x32x16_bf16 v[16:31], v[204:207], v[208:211], v[16:31]
	ds_write_b128 v171, v[242:245] offset:46080
	v_mfma_f32_32x32x16_bf16 v[0:15], v[204:207], v[212:215], v[0:15]
	ds_write_b128 v171, v[246:249] offset:55296
	ds_write_b128 v171, v[250:253] offset:64512
	s_waitcnt lgkmcnt(8)
	v_mfma_f32_32x32x16_bf16 v[112:127], v[128:131], v[144:147], v[112:127]
	ds_read_b128 v[208:211], v254 offset:32
	v_mfma_f32_32x32x16_bf16 v[96:111], v[128:131], v[148:151], v[96:111]
	ds_read_b128 v[212:215], v254 offset:4640
	ds_read_b128 v[192:195], v175 offset:32
	v_mfma_f32_32x32x16_bf16 v[80:95], v[132:135], v[144:147], v[80:95]
	ds_read_b128 v[196:199], v175 offset:4640
	ds_read_b128 v[200:203], v175 offset:9248
	v_mfma_f32_32x32x16_bf16 v[64:79], v[132:135], v[148:151], v[64:79]
	ds_read_b128 v[204:207], v175 offset:13856
	buffer_load_dwordx4 v[162:165], v160, s[48:51], 0 offen
	v_mfma_f32_32x32x16_bf16 v[48:63], v[136:139], v[144:147], v[48:63]
	buffer_load_dwordx4 v[166:169], v160, s[48:51], s46 offen
	buffer_load_dwordx4 v[176:179], v160, s[48:51], s47 offen
	v_mfma_f32_32x32x16_bf16 v[32:47], v[136:139], v[148:151], v[32:47]
	buffer_load_dwordx4 v[180:183], v160, s[48:51], s58 offen
	buffer_load_dwordx4 v[184:187], v160, s[52:55], 0 offen
	v_mfma_f32_32x32x16_bf16 v[16:31], v[140:143], v[144:147], v[16:31]
	buffer_load_dwordx4 v[242:245], v160, s[52:55], s46 offen
	buffer_load_dwordx4 v[246:249], v160, s[52:55], s47 offen
	v_mfma_f32_32x32x16_bf16 v[0:15], v[140:143], v[148:151], v[0:15]
	buffer_load_dwordx4 v[250:253], v160, s[52:55], s58 offen
	v_add_u32_e32 v160, 0x80, v160
	s_waitcnt lgkmcnt(0)
	v_mfma_f32_32x32x16_bf16 v[112:127], v[192:195], v[208:211], v[112:127]
	v_mfma_f32_32x32x16_bf16 v[96:111], v[192:195], v[212:215], v[96:111]
	ds_read_b128 v[144:147], v254 offset:64
	v_mfma_f32_32x32x16_bf16 v[80:95], v[196:199], v[208:211], v[80:95]
	ds_read_b128 v[148:151], v254 offset:4672
	v_mfma_f32_32x32x16_bf16 v[64:79], v[196:199], v[212:215], v[64:79]
	ds_read_b128 v[128:131], v175 offset:64
	v_mfma_f32_32x32x16_bf16 v[48:63], v[200:203], v[208:211], v[48:63]
	v_mfma_f32_32x32x16_bf16 v[32:47], v[200:203], v[212:215], v[32:47]
	ds_read_b128 v[132:135], v175 offset:4672
	v_mfma_f32_32x32x16_bf16 v[16:31], v[204:207], v[208:211], v[16:31]
	ds_read_b128 v[136:139], v175 offset:9280
	v_mfma_f32_32x32x16_bf16 v[0:15], v[204:207], v[212:215], v[0:15]
	ds_read_b128 v[140:143], v175 offset:13888
	s_waitcnt lgkmcnt(0)
	v_mfma_f32_32x32x16_bf16 v[112:127], v[128:131], v[144:147], v[112:127]
	v_mfma_f32_32x32x16_bf16 v[96:111], v[128:131], v[148:151], v[96:111]
	ds_read_b128 v[208:211], v254 offset:96
	v_mfma_f32_32x32x16_bf16 v[80:95], v[132:135], v[144:147], v[80:95]
	ds_read_b128 v[212:215], v254 offset:4704
	v_mfma_f32_32x32x16_bf16 v[64:79], v[132:135], v[148:151], v[64:79]
	ds_read_b128 v[192:195], v175 offset:96
	v_mfma_f32_32x32x16_bf16 v[48:63], v[136:139], v[144:147], v[48:63]
	v_mfma_f32_32x32x16_bf16 v[32:47], v[136:139], v[148:151], v[32:47]
	ds_read_b128 v[196:199], v175 offset:4704
	v_mfma_f32_32x32x16_bf16 v[16:31], v[140:143], v[144:147], v[16:31]
	ds_read_b128 v[200:203], v175 offset:9312
	v_mfma_f32_32x32x16_bf16 v[0:15], v[140:143], v[148:151], v[0:15]
	ds_read_b128 v[204:207], v175 offset:13920
	s_waitcnt lgkmcnt(0)
	s_barrier
	ds_read_b128 v[144:147], v254 offset:36864
	ds_read_b128 v[148:151], v254 offset:41472
	ds_read_b128 v[128:131], v175 offset:36864
	ds_read_b128 v[132:135], v175 offset:41472
	ds_read_b128 v[136:139], v175 offset:46080
	ds_read_b128 v[140:143], v175 offset:50688
	v_mfma_f32_32x32x16_bf16 v[112:127], v[192:195], v[208:211], v[112:127]
	s_waitcnt vmcnt(8)
	v_mfma_f32_32x32x16_bf16 v[96:111], v[192:195], v[212:215], v[96:111]
	ds_write_b128 v170, v[216:219] offset:0
	v_mfma_f32_32x32x16_bf16 v[80:95], v[196:199], v[208:211], v[80:95]
	ds_write_b128 v170, v[220:223] offset:9216
	v_mfma_f32_32x32x16_bf16 v[64:79], v[196:199], v[212:215], v[64:79]
	ds_write_b128 v170, v[224:227] offset:18432
	v_mfma_f32_32x32x16_bf16 v[48:63], v[200:203], v[208:211], v[48:63]
	ds_write_b128 v170, v[228:231] offset:27648
	v_mfma_f32_32x32x16_bf16 v[32:47], v[200:203], v[212:215], v[32:47]
	ds_write_b128 v171, v[232:235] offset:0
	v_mfma_f32_32x32x16_bf16 v[16:31], v[204:207], v[208:211], v[16:31]
	ds_write_b128 v171, v[236:239] offset:9216
	v_mfma_f32_32x32x16_bf16 v[0:15], v[204:207], v[212:215], v[0:15]
	ds_write_b128 v171, v[152:155] offset:18432
	ds_write_b128 v171, v[156:159] offset:27648
	s_waitcnt lgkmcnt(8)
	v_mfma_f32_32x32x16_bf16 v[112:127], v[128:131], v[144:147], v[112:127]
	v_mfma_f32_32x32x16_bf16 v[96:111], v[128:131], v[148:151], v[96:111]
	ds_read_b128 v[208:211], v254 offset:36896
	v_mfma_f32_32x32x16_bf16 v[80:95], v[132:135], v[144:147], v[80:95]
	ds_read_b128 v[212:215], v254 offset:41504
	v_mfma_f32_32x32x16_bf16 v[64:79], v[132:135], v[148:151], v[64:79]
	ds_read_b128 v[192:195], v175 offset:36896
	v_mfma_f32_32x32x16_bf16 v[48:63], v[136:139], v[144:147], v[48:63]
	v_mfma_f32_32x32x16_bf16 v[32:47], v[136:139], v[148:151], v[32:47]
	ds_read_b128 v[196:199], v175 offset:41504
	v_mfma_f32_32x32x16_bf16 v[16:31], v[140:143], v[144:147], v[16:31]
	ds_read_b128 v[200:203], v175 offset:46112
	v_mfma_f32_32x32x16_bf16 v[0:15], v[140:143], v[148:151], v[0:15]
	ds_read_b128 v[204:207], v175 offset:50720
	s_waitcnt lgkmcnt(0)
	v_mfma_f32_32x32x16_bf16 v[112:127], v[192:195], v[208:211], v[112:127]
	v_mfma_f32_32x32x16_bf16 v[96:111], v[192:195], v[212:215], v[96:111]
	ds_read_b128 v[144:147], v254 offset:36928
	v_mfma_f32_32x32x16_bf16 v[80:95], v[196:199], v[208:211], v[80:95]
	ds_read_b128 v[148:151], v254 offset:41536
	v_mfma_f32_32x32x16_bf16 v[64:79], v[196:199], v[212:215], v[64:79]
	ds_read_b128 v[128:131], v175 offset:36928
	v_mfma_f32_32x32x16_bf16 v[48:63], v[200:203], v[208:211], v[48:63]
	v_mfma_f32_32x32x16_bf16 v[32:47], v[200:203], v[212:215], v[32:47]
	ds_read_b128 v[132:135], v175 offset:41536
	v_mfma_f32_32x32x16_bf16 v[16:31], v[204:207], v[208:211], v[16:31]
	ds_read_b128 v[136:139], v175 offset:46144
	v_mfma_f32_32x32x16_bf16 v[0:15], v[204:207], v[212:215], v[0:15]
	ds_read_b128 v[140:143], v175 offset:50752
	s_waitcnt lgkmcnt(0)
	v_mfma_f32_32x32x16_bf16 v[112:127], v[128:131], v[144:147], v[112:127]
	v_mfma_f32_32x32x16_bf16 v[96:111], v[128:131], v[148:151], v[96:111]
	ds_read_b128 v[208:211], v254 offset:36960
	v_mfma_f32_32x32x16_bf16 v[80:95], v[132:135], v[144:147], v[80:95]
	ds_read_b128 v[212:215], v254 offset:41568
	v_mfma_f32_32x32x16_bf16 v[64:79], v[132:135], v[148:151], v[64:79]
	ds_read_b128 v[192:195], v175 offset:36960
	v_mfma_f32_32x32x16_bf16 v[48:63], v[136:139], v[144:147], v[48:63]
	v_mfma_f32_32x32x16_bf16 v[32:47], v[136:139], v[148:151], v[32:47]
	ds_read_b128 v[196:199], v175 offset:41568
	v_mfma_f32_32x32x16_bf16 v[16:31], v[140:143], v[144:147], v[16:31]
	ds_read_b128 v[200:203], v175 offset:46176
	v_mfma_f32_32x32x16_bf16 v[0:15], v[140:143], v[148:151], v[0:15]
	ds_read_b128 v[204:207], v175 offset:50784
	s_waitcnt lgkmcnt(0)
	s_barrier
	ds_read_b128 v[144:147], v254 offset:0
	ds_read_b128 v[148:151], v254 offset:4608
	ds_read_b128 v[128:131], v175 offset:0
	ds_read_b128 v[132:135], v175 offset:4608
	ds_read_b128 v[136:139], v175 offset:9216
	ds_read_b128 v[140:143], v175 offset:13824
	v_mfma_f32_32x32x16_bf16 v[112:127], v[192:195], v[208:211], v[112:127]
	s_waitcnt vmcnt(0)
	v_mfma_f32_32x32x16_bf16 v[96:111], v[192:195], v[212:215], v[96:111]
	ds_write_b128 v170, v[162:165] offset:36864
	v_mfma_f32_32x32x16_bf16 v[80:95], v[196:199], v[208:211], v[80:95]
	ds_write_b128 v170, v[166:169] offset:46080
	v_mfma_f32_32x32x16_bf16 v[64:79], v[196:199], v[212:215], v[64:79]
	ds_write_b128 v170, v[176:179] offset:55296
	v_mfma_f32_32x32x16_bf16 v[48:63], v[200:203], v[208:211], v[48:63]
	ds_write_b128 v170, v[180:183] offset:64512
	v_mfma_f32_32x32x16_bf16 v[32:47], v[200:203], v[212:215], v[32:47]
	ds_write_b128 v171, v[184:187] offset:36864
	v_mfma_f32_32x32x16_bf16 v[16:31], v[204:207], v[208:211], v[16:31]
	ds_write_b128 v171, v[242:245] offset:46080
	v_mfma_f32_32x32x16_bf16 v[0:15], v[204:207], v[212:215], v[0:15]
	ds_write_b128 v171, v[246:249] offset:55296
	ds_write_b128 v171, v[250:253] offset:64512
	s_waitcnt lgkmcnt(8)
	v_mfma_f32_32x32x16_bf16 v[112:127], v[128:131], v[144:147], v[112:127]
	v_mfma_f32_32x32x16_bf16 v[96:111], v[128:131], v[148:151], v[96:111]
	ds_read_b128 v[208:211], v254 offset:32
	v_mfma_f32_32x32x16_bf16 v[80:95], v[132:135], v[144:147], v[80:95]
	ds_read_b128 v[212:215], v254 offset:4640
	v_mfma_f32_32x32x16_bf16 v[64:79], v[132:135], v[148:151], v[64:79]
	ds_read_b128 v[192:195], v175 offset:32
	v_mfma_f32_32x32x16_bf16 v[48:63], v[136:139], v[144:147], v[48:63]
	v_mfma_f32_32x32x16_bf16 v[32:47], v[136:139], v[148:151], v[32:47]
	ds_read_b128 v[196:199], v175 offset:4640
	v_mfma_f32_32x32x16_bf16 v[16:31], v[140:143], v[144:147], v[16:31]
	ds_read_b128 v[200:203], v175 offset:9248
	v_mfma_f32_32x32x16_bf16 v[0:15], v[140:143], v[148:151], v[0:15]
	ds_read_b128 v[204:207], v175 offset:13856
	s_waitcnt lgkmcnt(0)
	v_mfma_f32_32x32x16_bf16 v[112:127], v[192:195], v[208:211], v[112:127]
	v_mfma_f32_32x32x16_bf16 v[96:111], v[192:195], v[212:215], v[96:111]
	ds_read_b128 v[144:147], v254 offset:64
	v_mfma_f32_32x32x16_bf16 v[80:95], v[196:199], v[208:211], v[80:95]
	ds_read_b128 v[148:151], v254 offset:4672
	v_mfma_f32_32x32x16_bf16 v[64:79], v[196:199], v[212:215], v[64:79]
	ds_read_b128 v[128:131], v175 offset:64
	v_mfma_f32_32x32x16_bf16 v[48:63], v[200:203], v[208:211], v[48:63]
	v_mfma_f32_32x32x16_bf16 v[32:47], v[200:203], v[212:215], v[32:47]
	ds_read_b128 v[132:135], v175 offset:4672
	v_mfma_f32_32x32x16_bf16 v[16:31], v[204:207], v[208:211], v[16:31]
	ds_read_b128 v[136:139], v175 offset:9280
	v_mfma_f32_32x32x16_bf16 v[0:15], v[204:207], v[212:215], v[0:15]
	ds_read_b128 v[140:143], v175 offset:13888
	s_waitcnt lgkmcnt(0)
	v_mfma_f32_32x32x16_bf16 v[112:127], v[128:131], v[144:147], v[112:127]
	v_mfma_f32_32x32x16_bf16 v[96:111], v[128:131], v[148:151], v[96:111]
	ds_read_b128 v[208:211], v254 offset:96
	v_mfma_f32_32x32x16_bf16 v[80:95], v[132:135], v[144:147], v[80:95]
	ds_read_b128 v[212:215], v254 offset:4704
	v_mfma_f32_32x32x16_bf16 v[64:79], v[132:135], v[148:151], v[64:79]
	ds_read_b128 v[192:195], v175 offset:96
	v_mfma_f32_32x32x16_bf16 v[48:63], v[136:139], v[144:147], v[48:63]
	v_mfma_f32_32x32x16_bf16 v[32:47], v[136:139], v[148:151], v[32:47]
	ds_read_b128 v[196:199], v175 offset:4704
	v_mfma_f32_32x32x16_bf16 v[16:31], v[140:143], v[144:147], v[16:31]
	ds_read_b128 v[200:203], v175 offset:9312
	v_mfma_f32_32x32x16_bf16 v[0:15], v[140:143], v[148:151], v[0:15]
	ds_read_b128 v[204:207], v175 offset:13920
	s_waitcnt lgkmcnt(0)
	s_barrier
	ds_read_b128 v[144:147], v254 offset:36864
	ds_read_b128 v[148:151], v254 offset:41472
	ds_read_b128 v[128:131], v175 offset:36864
	ds_read_b128 v[132:135], v175 offset:41472
	ds_read_b128 v[136:139], v175 offset:46080
	ds_read_b128 v[140:143], v175 offset:50688
	v_mfma_f32_32x32x16_bf16 v[112:127], v[192:195], v[208:211], v[112:127]
	v_mfma_f32_32x32x16_bf16 v[96:111], v[192:195], v[212:215], v[96:111]
	v_mfma_f32_32x32x16_bf16 v[80:95], v[196:199], v[208:211], v[80:95]
	v_mfma_f32_32x32x16_bf16 v[64:79], v[196:199], v[212:215], v[64:79]
	v_mfma_f32_32x32x16_bf16 v[48:63], v[200:203], v[208:211], v[48:63]
	v_mfma_f32_32x32x16_bf16 v[32:47], v[200:203], v[212:215], v[32:47]
	v_mfma_f32_32x32x16_bf16 v[16:31], v[204:207], v[208:211], v[16:31]
	v_mfma_f32_32x32x16_bf16 v[0:15], v[204:207], v[212:215], v[0:15]
	s_waitcnt lgkmcnt(0)
	v_mfma_f32_32x32x16_bf16 v[112:127], v[128:131], v[144:147], v[112:127]
	v_mfma_f32_32x32x16_bf16 v[96:111], v[128:131], v[148:151], v[96:111]
	ds_read_b128 v[208:211], v254 offset:36896
	v_mfma_f32_32x32x16_bf16 v[80:95], v[132:135], v[144:147], v[80:95]
	ds_read_b128 v[212:215], v254 offset:41504
	v_mfma_f32_32x32x16_bf16 v[64:79], v[132:135], v[148:151], v[64:79]
	ds_read_b128 v[192:195], v175 offset:36896
	v_mfma_f32_32x32x16_bf16 v[48:63], v[136:139], v[144:147], v[48:63]
	v_mfma_f32_32x32x16_bf16 v[32:47], v[136:139], v[148:151], v[32:47]
	ds_read_b128 v[196:199], v175 offset:41504
	v_mfma_f32_32x32x16_bf16 v[16:31], v[140:143], v[144:147], v[16:31]
	ds_read_b128 v[200:203], v175 offset:46112
	v_mfma_f32_32x32x16_bf16 v[0:15], v[140:143], v[148:151], v[0:15]
	ds_read_b128 v[204:207], v175 offset:50720
	s_waitcnt lgkmcnt(0)
	v_mfma_f32_32x32x16_bf16 v[112:127], v[192:195], v[208:211], v[112:127]
	v_mfma_f32_32x32x16_bf16 v[96:111], v[192:195], v[212:215], v[96:111]
	ds_read_b128 v[144:147], v254 offset:36928
	v_mfma_f32_32x32x16_bf16 v[80:95], v[196:199], v[208:211], v[80:95]
	ds_read_b128 v[148:151], v254 offset:41536
	v_mfma_f32_32x32x16_bf16 v[64:79], v[196:199], v[212:215], v[64:79]
	ds_read_b128 v[128:131], v175 offset:36928
	v_mfma_f32_32x32x16_bf16 v[48:63], v[200:203], v[208:211], v[48:63]
	v_mfma_f32_32x32x16_bf16 v[32:47], v[200:203], v[212:215], v[32:47]
	ds_read_b128 v[132:135], v175 offset:41536
	v_mfma_f32_32x32x16_bf16 v[16:31], v[204:207], v[208:211], v[16:31]
	ds_read_b128 v[136:139], v175 offset:46144
	v_mfma_f32_32x32x16_bf16 v[0:15], v[204:207], v[212:215], v[0:15]
	ds_read_b128 v[140:143], v175 offset:50752
	s_waitcnt lgkmcnt(0)
	v_mfma_f32_32x32x16_bf16 v[112:127], v[128:131], v[144:147], v[112:127]
	v_mfma_f32_32x32x16_bf16 v[96:111], v[128:131], v[148:151], v[96:111]
	ds_read_b128 v[208:211], v254 offset:36960
	v_mfma_f32_32x32x16_bf16 v[80:95], v[132:135], v[144:147], v[80:95]
	ds_read_b128 v[212:215], v254 offset:41568
	v_mfma_f32_32x32x16_bf16 v[64:79], v[132:135], v[148:151], v[64:79]
	ds_read_b128 v[192:195], v175 offset:36960
	v_mfma_f32_32x32x16_bf16 v[48:63], v[136:139], v[144:147], v[48:63]
	v_mfma_f32_32x32x16_bf16 v[32:47], v[136:139], v[148:151], v[32:47]
	ds_read_b128 v[196:199], v175 offset:41568
	v_mfma_f32_32x32x16_bf16 v[16:31], v[140:143], v[144:147], v[16:31]
	ds_read_b128 v[200:203], v175 offset:46176
	v_mfma_f32_32x32x16_bf16 v[0:15], v[140:143], v[148:151], v[0:15]
	ds_read_b128 v[204:207], v175 offset:50784
	s_waitcnt lgkmcnt(0)
	s_barrier
	v_mfma_f32_32x32x16_bf16 v[112:127], v[192:195], v[208:211], v[112:127]
	v_mfma_f32_32x32x16_bf16 v[96:111], v[192:195], v[212:215], v[96:111]
	v_mfma_f32_32x32x16_bf16 v[80:95], v[196:199], v[208:211], v[80:95]
	v_mfma_f32_32x32x16_bf16 v[64:79], v[196:199], v[212:215], v[64:79]
	v_mfma_f32_32x32x16_bf16 v[48:63], v[200:203], v[208:211], v[48:63]
	v_mfma_f32_32x32x16_bf16 v[32:47], v[200:203], v[212:215], v[32:47]
	v_mfma_f32_32x32x16_bf16 v[16:31], v[204:207], v[208:211], v[16:31]
	v_mfma_f32_32x32x16_bf16 v[0:15], v[204:207], v[212:215], v[0:15]
	s_nop 7
	s_nop 7
	s_mul_i32 s100, s64, 0x8000
	s_mul_hi_u32 s101, s64, 0x8000
	s_add_u32 s100, s100, 0x17c24000
	s_addc_u32 s101, s101, 0
	s_add_u32 s96, s92, s100
	s_addc_u32 s97, s93, s101
	s_and_b32 s97, s97, 0xffff
	s_mov_b32 s98, 0x800000
	s_mov_b32 s99, 0x20000
	s_movk_i32 s46, 0x7fff
	v_and_b32_e32 v132, 31, v190
	v_bfe_u32 v133, v190, 5, 1
	v_bfe_u32 v134, v190, 6, 2
	v_bfe_u32 v135, v190, 8, 1
	v_lshl_add_u32 v132, v134, 6, v132
	v_add_u32_e32 v132, s82, v132
	v_lshlrev_b32_e32 v132, 1, v132
	v_lshlrev_b32_e32 v135, 7, v135
	v_lshl_add_u32 v135, v133, 2, v135
	s_mov_b32 s47, 0x8000
	v_mul_lo_u32 v135, s47, v135
	v_add_u32_e32 v128, v135, v132
	v_add_u32_e32 v129, 0x8000, v128
	v_add_u32_e32 v130, 0x10000, v128
	v_add_u32_e32 v131, 0x18000, v128
	v_bfe_u32 v136, v112, 16, 1
	v_bfe_u32 v137, v113, 16, 1
	v_bfe_u32 v138, v114, 16, 1
	v_bfe_u32 v139, v115, 16, 1
	v_add3_u32 v112, v112, v136, s46
	v_add3_u32 v113, v113, v137, s46
	v_add3_u32 v114, v114, v138, s46
	v_add3_u32 v115, v115, v139, s46
	s_mov_b32 s101, 0x0
	buffer_store_short_d16_hi v112, v128, s[96:99], s101 offen
	buffer_store_short_d16_hi v113, v129, s[96:99], s101 offen
	buffer_store_short_d16_hi v114, v130, s[96:99], s101 offen
	buffer_store_short_d16_hi v115, v131, s[96:99], s101 offen
	v_bfe_u32 v136, v116, 16, 1
	v_bfe_u32 v137, v117, 16, 1
	v_bfe_u32 v138, v118, 16, 1
	v_bfe_u32 v139, v119, 16, 1
	v_add3_u32 v116, v116, v136, s46
	v_add3_u32 v117, v117, v137, s46
	v_add3_u32 v118, v118, v138, s46
	v_add3_u32 v119, v119, v139, s46
	s_mov_b32 s101, 0x40000
	buffer_store_short_d16_hi v116, v128, s[96:99], s101 offen
	buffer_store_short_d16_hi v117, v129, s[96:99], s101 offen
	buffer_store_short_d16_hi v118, v130, s[96:99], s101 offen
	buffer_store_short_d16_hi v119, v131, s[96:99], s101 offen
	v_bfe_u32 v136, v120, 16, 1
	v_bfe_u32 v137, v121, 16, 1
	v_bfe_u32 v138, v122, 16, 1
	v_bfe_u32 v139, v123, 16, 1
	v_add3_u32 v120, v120, v136, s46
	v_add3_u32 v121, v121, v137, s46
	v_add3_u32 v122, v122, v138, s46
	v_add3_u32 v123, v123, v139, s46
	s_mov_b32 s101, 0x80000
	buffer_store_short_d16_hi v120, v128, s[96:99], s101 offen
	buffer_store_short_d16_hi v121, v129, s[96:99], s101 offen
	buffer_store_short_d16_hi v122, v130, s[96:99], s101 offen
	buffer_store_short_d16_hi v123, v131, s[96:99], s101 offen
	v_bfe_u32 v136, v124, 16, 1
	v_bfe_u32 v137, v125, 16, 1
	v_bfe_u32 v138, v126, 16, 1
	v_bfe_u32 v139, v127, 16, 1
	v_add3_u32 v124, v124, v136, s46
	v_add3_u32 v125, v125, v137, s46
	v_add3_u32 v126, v126, v138, s46
	v_add3_u32 v127, v127, v139, s46
	s_mov_b32 s101, 0xc0000
	buffer_store_short_d16_hi v124, v128, s[96:99], s101 offen
	buffer_store_short_d16_hi v125, v129, s[96:99], s101 offen
	buffer_store_short_d16_hi v126, v130, s[96:99], s101 offen
	buffer_store_short_d16_hi v127, v131, s[96:99], s101 offen
	v_bfe_u32 v136, v96, 16, 1
	v_bfe_u32 v137, v97, 16, 1
	v_bfe_u32 v138, v98, 16, 1
	v_bfe_u32 v139, v99, 16, 1
	v_add3_u32 v96, v96, v136, s46
	v_add3_u32 v97, v97, v137, s46
	v_add3_u32 v98, v98, v138, s46
	v_add3_u32 v99, v99, v139, s46
	s_mov_b32 s101, 0x0
	buffer_store_short_d16_hi v96, v128, s[96:99], s101 offen offset:64
	buffer_store_short_d16_hi v97, v129, s[96:99], s101 offen offset:64
	buffer_store_short_d16_hi v98, v130, s[96:99], s101 offen offset:64
	buffer_store_short_d16_hi v99, v131, s[96:99], s101 offen offset:64
	v_bfe_u32 v136, v100, 16, 1
	v_bfe_u32 v137, v101, 16, 1
	v_bfe_u32 v138, v102, 16, 1
	v_bfe_u32 v139, v103, 16, 1
	v_add3_u32 v100, v100, v136, s46
	v_add3_u32 v101, v101, v137, s46
	v_add3_u32 v102, v102, v138, s46
	v_add3_u32 v103, v103, v139, s46
	s_mov_b32 s101, 0x40000
	buffer_store_short_d16_hi v100, v128, s[96:99], s101 offen offset:64
	buffer_store_short_d16_hi v101, v129, s[96:99], s101 offen offset:64
	buffer_store_short_d16_hi v102, v130, s[96:99], s101 offen offset:64
	buffer_store_short_d16_hi v103, v131, s[96:99], s101 offen offset:64
	v_bfe_u32 v136, v104, 16, 1
	v_bfe_u32 v137, v105, 16, 1
	v_bfe_u32 v138, v106, 16, 1
	v_bfe_u32 v139, v107, 16, 1
	v_add3_u32 v104, v104, v136, s46
	v_add3_u32 v105, v105, v137, s46
	v_add3_u32 v106, v106, v138, s46
	v_add3_u32 v107, v107, v139, s46
	s_mov_b32 s101, 0x80000
	buffer_store_short_d16_hi v104, v128, s[96:99], s101 offen offset:64
	buffer_store_short_d16_hi v105, v129, s[96:99], s101 offen offset:64
	buffer_store_short_d16_hi v106, v130, s[96:99], s101 offen offset:64
	buffer_store_short_d16_hi v107, v131, s[96:99], s101 offen offset:64
	v_bfe_u32 v136, v108, 16, 1
	v_bfe_u32 v137, v109, 16, 1
	v_bfe_u32 v138, v110, 16, 1
	v_bfe_u32 v139, v111, 16, 1
	v_add3_u32 v108, v108, v136, s46
	v_add3_u32 v109, v109, v137, s46
	v_add3_u32 v110, v110, v138, s46
	v_add3_u32 v111, v111, v139, s46
	s_mov_b32 s101, 0xc0000
	buffer_store_short_d16_hi v108, v128, s[96:99], s101 offen offset:64
	buffer_store_short_d16_hi v109, v129, s[96:99], s101 offen offset:64
	buffer_store_short_d16_hi v110, v130, s[96:99], s101 offen offset:64
	buffer_store_short_d16_hi v111, v131, s[96:99], s101 offen offset:64
	v_bfe_u32 v136, v80, 16, 1
	v_bfe_u32 v137, v81, 16, 1
	v_bfe_u32 v138, v82, 16, 1
	v_bfe_u32 v139, v83, 16, 1
	v_add3_u32 v80, v80, v136, s46
	v_add3_u32 v81, v81, v137, s46
	v_add3_u32 v82, v82, v138, s46
	v_add3_u32 v83, v83, v139, s46
	s_mov_b32 s101, 0x100000
	buffer_store_short_d16_hi v80, v128, s[96:99], s101 offen
	buffer_store_short_d16_hi v81, v129, s[96:99], s101 offen
	buffer_store_short_d16_hi v82, v130, s[96:99], s101 offen
	buffer_store_short_d16_hi v83, v131, s[96:99], s101 offen
	v_bfe_u32 v136, v84, 16, 1
	v_bfe_u32 v137, v85, 16, 1
	v_bfe_u32 v138, v86, 16, 1
	v_bfe_u32 v139, v87, 16, 1
	v_add3_u32 v84, v84, v136, s46
	v_add3_u32 v85, v85, v137, s46
	v_add3_u32 v86, v86, v138, s46
	v_add3_u32 v87, v87, v139, s46
	s_mov_b32 s101, 0x140000
	buffer_store_short_d16_hi v84, v128, s[96:99], s101 offen
	buffer_store_short_d16_hi v85, v129, s[96:99], s101 offen
	buffer_store_short_d16_hi v86, v130, s[96:99], s101 offen
	buffer_store_short_d16_hi v87, v131, s[96:99], s101 offen
	v_bfe_u32 v136, v88, 16, 1
	v_bfe_u32 v137, v89, 16, 1
	v_bfe_u32 v138, v90, 16, 1
	v_bfe_u32 v139, v91, 16, 1
	v_add3_u32 v88, v88, v136, s46
	v_add3_u32 v89, v89, v137, s46
	v_add3_u32 v90, v90, v138, s46
	v_add3_u32 v91, v91, v139, s46
	s_mov_b32 s101, 0x180000
	buffer_store_short_d16_hi v88, v128, s[96:99], s101 offen
	buffer_store_short_d16_hi v89, v129, s[96:99], s101 offen
	buffer_store_short_d16_hi v90, v130, s[96:99], s101 offen
	buffer_store_short_d16_hi v91, v131, s[96:99], s101 offen
	v_bfe_u32 v136, v92, 16, 1
	v_bfe_u32 v137, v93, 16, 1
	v_bfe_u32 v138, v94, 16, 1
	v_bfe_u32 v139, v95, 16, 1
	v_add3_u32 v92, v92, v136, s46
	v_add3_u32 v93, v93, v137, s46
	v_add3_u32 v94, v94, v138, s46
	v_add3_u32 v95, v95, v139, s46
	s_mov_b32 s101, 0x1c0000
	buffer_store_short_d16_hi v92, v128, s[96:99], s101 offen
	buffer_store_short_d16_hi v93, v129, s[96:99], s101 offen
	buffer_store_short_d16_hi v94, v130, s[96:99], s101 offen
	buffer_store_short_d16_hi v95, v131, s[96:99], s101 offen
	v_bfe_u32 v136, v64, 16, 1
	v_bfe_u32 v137, v65, 16, 1
	v_bfe_u32 v138, v66, 16, 1
	v_bfe_u32 v139, v67, 16, 1
	v_add3_u32 v64, v64, v136, s46
	v_add3_u32 v65, v65, v137, s46
	v_add3_u32 v66, v66, v138, s46
	v_add3_u32 v67, v67, v139, s46
	s_mov_b32 s101, 0x100000
	buffer_store_short_d16_hi v64, v128, s[96:99], s101 offen offset:64
	buffer_store_short_d16_hi v65, v129, s[96:99], s101 offen offset:64
	buffer_store_short_d16_hi v66, v130, s[96:99], s101 offen offset:64
	buffer_store_short_d16_hi v67, v131, s[96:99], s101 offen offset:64
	v_bfe_u32 v136, v68, 16, 1
	v_bfe_u32 v137, v69, 16, 1
	v_bfe_u32 v138, v70, 16, 1
	v_bfe_u32 v139, v71, 16, 1
	v_add3_u32 v68, v68, v136, s46
	v_add3_u32 v69, v69, v137, s46
	v_add3_u32 v70, v70, v138, s46
	v_add3_u32 v71, v71, v139, s46
	s_mov_b32 s101, 0x140000
	buffer_store_short_d16_hi v68, v128, s[96:99], s101 offen offset:64
	buffer_store_short_d16_hi v69, v129, s[96:99], s101 offen offset:64
	buffer_store_short_d16_hi v70, v130, s[96:99], s101 offen offset:64
	buffer_store_short_d16_hi v71, v131, s[96:99], s101 offen offset:64
	v_bfe_u32 v136, v72, 16, 1
	v_bfe_u32 v137, v73, 16, 1
	v_bfe_u32 v138, v74, 16, 1
	v_bfe_u32 v139, v75, 16, 1
	v_add3_u32 v72, v72, v136, s46
	v_add3_u32 v73, v73, v137, s46
	v_add3_u32 v74, v74, v138, s46
	v_add3_u32 v75, v75, v139, s46
	s_mov_b32 s101, 0x180000
	buffer_store_short_d16_hi v72, v128, s[96:99], s101 offen offset:64
	buffer_store_short_d16_hi v73, v129, s[96:99], s101 offen offset:64
	buffer_store_short_d16_hi v74, v130, s[96:99], s101 offen offset:64
	buffer_store_short_d16_hi v75, v131, s[96:99], s101 offen offset:64
	v_bfe_u32 v136, v76, 16, 1
	v_bfe_u32 v137, v77, 16, 1
	v_bfe_u32 v138, v78, 16, 1
	v_bfe_u32 v139, v79, 16, 1
	v_add3_u32 v76, v76, v136, s46
	v_add3_u32 v77, v77, v137, s46
	v_add3_u32 v78, v78, v138, s46
	v_add3_u32 v79, v79, v139, s46
	s_mov_b32 s101, 0x1c0000
	buffer_store_short_d16_hi v76, v128, s[96:99], s101 offen offset:64
	buffer_store_short_d16_hi v77, v129, s[96:99], s101 offen offset:64
	buffer_store_short_d16_hi v78, v130, s[96:99], s101 offen offset:64
	buffer_store_short_d16_hi v79, v131, s[96:99], s101 offen offset:64
	v_bfe_u32 v136, v48, 16, 1
	v_bfe_u32 v137, v49, 16, 1
	v_bfe_u32 v138, v50, 16, 1
	v_bfe_u32 v139, v51, 16, 1
	v_add3_u32 v48, v48, v136, s46
	v_add3_u32 v49, v49, v137, s46
	v_add3_u32 v50, v50, v138, s46
	v_add3_u32 v51, v51, v139, s46
	s_mov_b32 s101, 0x200000
	buffer_store_short_d16_hi v48, v128, s[96:99], s101 offen
	buffer_store_short_d16_hi v49, v129, s[96:99], s101 offen
	buffer_store_short_d16_hi v50, v130, s[96:99], s101 offen
	buffer_store_short_d16_hi v51, v131, s[96:99], s101 offen
	v_bfe_u32 v136, v52, 16, 1
	v_bfe_u32 v137, v53, 16, 1
	v_bfe_u32 v138, v54, 16, 1
	v_bfe_u32 v139, v55, 16, 1
	v_add3_u32 v52, v52, v136, s46
	v_add3_u32 v53, v53, v137, s46
	v_add3_u32 v54, v54, v138, s46
	v_add3_u32 v55, v55, v139, s46
	s_mov_b32 s101, 0x240000
	buffer_store_short_d16_hi v52, v128, s[96:99], s101 offen
	buffer_store_short_d16_hi v53, v129, s[96:99], s101 offen
	buffer_store_short_d16_hi v54, v130, s[96:99], s101 offen
	buffer_store_short_d16_hi v55, v131, s[96:99], s101 offen
	v_bfe_u32 v136, v56, 16, 1
	v_bfe_u32 v137, v57, 16, 1
	v_bfe_u32 v138, v58, 16, 1
	v_bfe_u32 v139, v59, 16, 1
	v_add3_u32 v56, v56, v136, s46
	v_add3_u32 v57, v57, v137, s46
	v_add3_u32 v58, v58, v138, s46
	v_add3_u32 v59, v59, v139, s46
	s_mov_b32 s101, 0x280000
	buffer_store_short_d16_hi v56, v128, s[96:99], s101 offen
	buffer_store_short_d16_hi v57, v129, s[96:99], s101 offen
	buffer_store_short_d16_hi v58, v130, s[96:99], s101 offen
	buffer_store_short_d16_hi v59, v131, s[96:99], s101 offen
	v_bfe_u32 v136, v60, 16, 1
	v_bfe_u32 v137, v61, 16, 1
	v_bfe_u32 v138, v62, 16, 1
	v_bfe_u32 v139, v63, 16, 1
	v_add3_u32 v60, v60, v136, s46
	v_add3_u32 v61, v61, v137, s46
	v_add3_u32 v62, v62, v138, s46
	v_add3_u32 v63, v63, v139, s46
	s_mov_b32 s101, 0x2c0000
	buffer_store_short_d16_hi v60, v128, s[96:99], s101 offen
	buffer_store_short_d16_hi v61, v129, s[96:99], s101 offen
	buffer_store_short_d16_hi v62, v130, s[96:99], s101 offen
	buffer_store_short_d16_hi v63, v131, s[96:99], s101 offen
	v_bfe_u32 v136, v32, 16, 1
	v_bfe_u32 v137, v33, 16, 1
	v_bfe_u32 v138, v34, 16, 1
	v_bfe_u32 v139, v35, 16, 1
	v_add3_u32 v32, v32, v136, s46
	v_add3_u32 v33, v33, v137, s46
	v_add3_u32 v34, v34, v138, s46
	v_add3_u32 v35, v35, v139, s46
	s_mov_b32 s101, 0x200000
	buffer_store_short_d16_hi v32, v128, s[96:99], s101 offen offset:64
	buffer_store_short_d16_hi v33, v129, s[96:99], s101 offen offset:64
	buffer_store_short_d16_hi v34, v130, s[96:99], s101 offen offset:64
	buffer_store_short_d16_hi v35, v131, s[96:99], s101 offen offset:64
	v_bfe_u32 v136, v36, 16, 1
	v_bfe_u32 v137, v37, 16, 1
	v_bfe_u32 v138, v38, 16, 1
	v_bfe_u32 v139, v39, 16, 1
	v_add3_u32 v36, v36, v136, s46
	v_add3_u32 v37, v37, v137, s46
	v_add3_u32 v38, v38, v138, s46
	v_add3_u32 v39, v39, v139, s46
	s_mov_b32 s101, 0x240000
	buffer_store_short_d16_hi v36, v128, s[96:99], s101 offen offset:64
	buffer_store_short_d16_hi v37, v129, s[96:99], s101 offen offset:64
	buffer_store_short_d16_hi v38, v130, s[96:99], s101 offen offset:64
	buffer_store_short_d16_hi v39, v131, s[96:99], s101 offen offset:64
	v_bfe_u32 v136, v40, 16, 1
	v_bfe_u32 v137, v41, 16, 1
	v_bfe_u32 v138, v42, 16, 1
	v_bfe_u32 v139, v43, 16, 1
	v_add3_u32 v40, v40, v136, s46
	v_add3_u32 v41, v41, v137, s46
	v_add3_u32 v42, v42, v138, s46
	v_add3_u32 v43, v43, v139, s46
	s_mov_b32 s101, 0x280000
	buffer_store_short_d16_hi v40, v128, s[96:99], s101 offen offset:64
	buffer_store_short_d16_hi v41, v129, s[96:99], s101 offen offset:64
	buffer_store_short_d16_hi v42, v130, s[96:99], s101 offen offset:64
	buffer_store_short_d16_hi v43, v131, s[96:99], s101 offen offset:64
	v_bfe_u32 v136, v44, 16, 1
	v_bfe_u32 v137, v45, 16, 1
	v_bfe_u32 v138, v46, 16, 1
	v_bfe_u32 v139, v47, 16, 1
	v_add3_u32 v44, v44, v136, s46
	v_add3_u32 v45, v45, v137, s46
	v_add3_u32 v46, v46, v138, s46
	v_add3_u32 v47, v47, v139, s46
	s_mov_b32 s101, 0x2c0000
	buffer_store_short_d16_hi v44, v128, s[96:99], s101 offen offset:64
	buffer_store_short_d16_hi v45, v129, s[96:99], s101 offen offset:64
	buffer_store_short_d16_hi v46, v130, s[96:99], s101 offen offset:64
	buffer_store_short_d16_hi v47, v131, s[96:99], s101 offen offset:64
	v_bfe_u32 v136, v16, 16, 1
	v_bfe_u32 v137, v17, 16, 1
	v_bfe_u32 v138, v18, 16, 1
	v_bfe_u32 v139, v19, 16, 1
	v_add3_u32 v16, v16, v136, s46
	v_add3_u32 v17, v17, v137, s46
	v_add3_u32 v18, v18, v138, s46
	v_add3_u32 v19, v19, v139, s46
	s_mov_b32 s101, 0x300000
	buffer_store_short_d16_hi v16, v128, s[96:99], s101 offen
	buffer_store_short_d16_hi v17, v129, s[96:99], s101 offen
	buffer_store_short_d16_hi v18, v130, s[96:99], s101 offen
	buffer_store_short_d16_hi v19, v131, s[96:99], s101 offen
	v_bfe_u32 v136, v20, 16, 1
	v_bfe_u32 v137, v21, 16, 1
	v_bfe_u32 v138, v22, 16, 1
	v_bfe_u32 v139, v23, 16, 1
	v_add3_u32 v20, v20, v136, s46
	v_add3_u32 v21, v21, v137, s46
	v_add3_u32 v22, v22, v138, s46
	v_add3_u32 v23, v23, v139, s46
	s_mov_b32 s101, 0x340000
	buffer_store_short_d16_hi v20, v128, s[96:99], s101 offen
	buffer_store_short_d16_hi v21, v129, s[96:99], s101 offen
	buffer_store_short_d16_hi v22, v130, s[96:99], s101 offen
	buffer_store_short_d16_hi v23, v131, s[96:99], s101 offen
	v_bfe_u32 v136, v24, 16, 1
	v_bfe_u32 v137, v25, 16, 1
	v_bfe_u32 v138, v26, 16, 1
	v_bfe_u32 v139, v27, 16, 1
	v_add3_u32 v24, v24, v136, s46
	v_add3_u32 v25, v25, v137, s46
	v_add3_u32 v26, v26, v138, s46
	v_add3_u32 v27, v27, v139, s46
	s_mov_b32 s101, 0x380000
	buffer_store_short_d16_hi v24, v128, s[96:99], s101 offen
	buffer_store_short_d16_hi v25, v129, s[96:99], s101 offen
	buffer_store_short_d16_hi v26, v130, s[96:99], s101 offen
	buffer_store_short_d16_hi v27, v131, s[96:99], s101 offen
	v_bfe_u32 v136, v28, 16, 1
	v_bfe_u32 v137, v29, 16, 1
	v_bfe_u32 v138, v30, 16, 1
	v_bfe_u32 v139, v31, 16, 1
	v_add3_u32 v28, v28, v136, s46
	v_add3_u32 v29, v29, v137, s46
	v_add3_u32 v30, v30, v138, s46
	v_add3_u32 v31, v31, v139, s46
	s_mov_b32 s101, 0x3c0000
	buffer_store_short_d16_hi v28, v128, s[96:99], s101 offen
	buffer_store_short_d16_hi v29, v129, s[96:99], s101 offen
	buffer_store_short_d16_hi v30, v130, s[96:99], s101 offen
	buffer_store_short_d16_hi v31, v131, s[96:99], s101 offen
	v_bfe_u32 v136, v0, 16, 1
	v_bfe_u32 v137, v1, 16, 1
	v_bfe_u32 v138, v2, 16, 1
	v_bfe_u32 v139, v3, 16, 1
	v_add3_u32 v0, v0, v136, s46
	v_add3_u32 v1, v1, v137, s46
	v_add3_u32 v2, v2, v138, s46
	v_add3_u32 v3, v3, v139, s46
	s_mov_b32 s101, 0x300000
	buffer_store_short_d16_hi v0, v128, s[96:99], s101 offen offset:64
	buffer_store_short_d16_hi v1, v129, s[96:99], s101 offen offset:64
	buffer_store_short_d16_hi v2, v130, s[96:99], s101 offen offset:64
	buffer_store_short_d16_hi v3, v131, s[96:99], s101 offen offset:64
	v_bfe_u32 v136, v4, 16, 1
	v_bfe_u32 v137, v5, 16, 1
	v_bfe_u32 v138, v6, 16, 1
	v_bfe_u32 v139, v7, 16, 1
	v_add3_u32 v4, v4, v136, s46
	v_add3_u32 v5, v5, v137, s46
	v_add3_u32 v6, v6, v138, s46
	v_add3_u32 v7, v7, v139, s46
	s_mov_b32 s101, 0x340000
	buffer_store_short_d16_hi v4, v128, s[96:99], s101 offen offset:64
	buffer_store_short_d16_hi v5, v129, s[96:99], s101 offen offset:64
	buffer_store_short_d16_hi v6, v130, s[96:99], s101 offen offset:64
	buffer_store_short_d16_hi v7, v131, s[96:99], s101 offen offset:64
	v_bfe_u32 v136, v8, 16, 1
	v_bfe_u32 v137, v9, 16, 1
	v_bfe_u32 v138, v10, 16, 1
	v_bfe_u32 v139, v11, 16, 1
	v_add3_u32 v8, v8, v136, s46
	v_add3_u32 v9, v9, v137, s46
	v_add3_u32 v10, v10, v138, s46
	v_add3_u32 v11, v11, v139, s46
	s_mov_b32 s101, 0x380000
	buffer_store_short_d16_hi v8, v128, s[96:99], s101 offen offset:64
	buffer_store_short_d16_hi v9, v129, s[96:99], s101 offen offset:64
	buffer_store_short_d16_hi v10, v130, s[96:99], s101 offen offset:64
	buffer_store_short_d16_hi v11, v131, s[96:99], s101 offen offset:64
	v_bfe_u32 v136, v12, 16, 1
	v_bfe_u32 v137, v13, 16, 1
	v_bfe_u32 v138, v14, 16, 1
	v_bfe_u32 v139, v15, 16, 1
	v_add3_u32 v12, v12, v136, s46
	v_add3_u32 v13, v13, v137, s46
	v_add3_u32 v14, v14, v138, s46
	v_add3_u32 v15, v15, v139, s46
	s_mov_b32 s101, 0x3c0000
	buffer_store_short_d16_hi v12, v128, s[96:99], s101 offen offset:64
	buffer_store_short_d16_hi v13, v129, s[96:99], s101 offen offset:64
	buffer_store_short_d16_hi v14, v130, s[96:99], s101 offen offset:64
	buffer_store_short_d16_hi v15, v131, s[96:99], s101 offen offset:64
	s_add_i32 s39, s39, s94
	s_cmpk_lt_i32 s39, 0x600
	s_cbranch_scc1 .Lgin1_tile
	s_branch .LBB0_1659
